# added: P5 residual rolling prefetch, scan partial-sum reads batched, attention unit order remapped so the P11-P12 barrier is XCD-local
# baseline (speedup 1.0000x reference)
.LBB0_457:
	v_lshl_add_u64 v[188:189], s[66:67], 0, v[170:171]
	s_mov_b32 s33, 0x15704000
	v_add_co_u32_e32 v88, vcc, s33, v188
	v_lshl_add_u64 v[184:185], s[66:67], 0, v[166:167]
	s_nop 0
	v_addc_co_u32_e32 v89, vcc, 0, v189, vcc
	v_add_co_u32_e32 v90, vcc, s82, v184
	v_lshl_add_u64 v[186:187], s[66:67], 0, v[168:169]
	s_nop 0
	v_addc_co_u32_e32 v91, vcc, 0, v185, vcc
	v_add_co_u32_e32 v92, vcc, s83, v184
	global_load_dwordx4 v[112:115], v[88:89], off
	global_load_dwordx4 v[116:119], v[90:91], off
	global_load_dwordx4 v[120:123], v[90:91], off offset:1024
	global_load_dwordx4 v[124:127], v[90:91], off offset:2048
	v_addc_co_u32_e32 v93, vcc, 0, v185, vcc
	global_load_dwordx4 v[128:131], v[90:91], off offset:3072
	global_load_dwordx4 v[100:103], v[92:93], off
	global_load_dwordx4 v[96:99], v[92:93], off offset:1024
	s_nop 0
	global_load_dwordx4 v[88:91], v[92:93], off offset:2048
	s_nop 0
	global_load_dwordx4 v[92:95], v[92:93], off offset:3072
	s_nop 0
	global_load_dwordx4 v[108:111], v[186:187], off offset:-1024
	global_load_dwordx4 v[104:107], v[186:187], off offset:-960
	s_add_i32 s96, s18, 3
	s_and_b32 s33, s96, 1
	s_lshl_b32 s54, s33, 15
	s_lshl_b32 s33, s33, 11
	s_add_i32 s33, s69, s33
	v_add_u32_e32 v201, s33, v163
	ds_read_b64_tr_b16 v[206:207], v201
	v_add_u32_e32 v202, 0x80, v201
	ds_read_b64_tr_b16 v[208:209], v202
	v_add_u32_e32 v203, 0x400, v201
	ds_read_b64_tr_b16 v[210:211], v203
	v_add_u32_e32 v204, 0x480, v201
	ds_read_b64_tr_b16 v[212:213], v204
	s_waitcnt lgkmcnt(0)
	v_cvt_pk_bf16_f32 v214, v132, v133
	v_cvt_pk_bf16_f32 v215, v134, v135
	v_cvt_pk_bf16_f32 v216, v136, v137
	v_cvt_pk_bf16_f32 v217, v138, v139
	s_add_i32 s33, s54, 0
	s_waitcnt vmcnt(31)
	v_mfma_f32_16x16x32_bf16 v[44:47], v[44:47], v[214:217], 0
	s_add_i32 s54, s68, s33
	s_add_i32 s18, s18, 4
	s_and_b32 s18, s18, 1
	s_waitcnt vmcnt(30)
	v_mfma_f32_16x16x32_bf16 v[52:55], v[52:55], v[214:217], 0
	s_waitcnt vmcnt(29)
	v_mfma_f32_16x16x32_bf16 v[28:31], v[28:31], v[214:217], 0
	s_waitcnt vmcnt(28)
	v_mfma_f32_16x16x32_bf16 v[20:23], v[20:23], v[214:217], 0
	v_cndmask_b32_e64 v215, v211, v207, s[4:5]
	v_cndmask_b32_e64 v214, v210, v206, s[4:5]
	v_cndmask_b32_e64 v217, v213, v209, s[4:5]
	v_cndmask_b32_e64 v216, v212, v208, s[4:5]
	s_nop 1
	v_mfma_f32_16x16x32_bf16 v[0:3], v[0:3], v[214:217], 0
	v_lshlrev_b32_e32 v215, 2, v149
	v_add_u32_e32 v205, s54, v215
	s_nop 5
	v_cndmask_b32_e64 v182, 0, v0, s[6:7]
	v_add_f32_e32 v44, v44, v182
	v_cndmask_b32_e64 v182, 0, v1, s[6:7]
	v_add_f32_e32 v45, v45, v182
	v_cndmask_b32_e64 v182, 0, v2, s[6:7]
	v_add_f32_e32 v46, v46, v182
	v_cndmask_b32_e64 v182, 0, v3, s[6:7]
	v_add_f32_e32 v47, v47, v182
	v_cndmask_b32_e64 v182, 0, v0, s[8:9]
	v_add_f32_e32 v52, v52, v182
	v_cndmask_b32_e64 v182, 0, v1, s[8:9]
	v_add_f32_e32 v53, v53, v182
	v_cndmask_b32_e64 v182, 0, v2, s[8:9]
	v_add_f32_e32 v54, v54, v182
	v_cndmask_b32_e64 v182, 0, v3, s[8:9]
	v_add_f32_e32 v55, v55, v182
	v_cndmask_b32_e64 v182, 0, v0, s[10:11]
	v_add_f32_e32 v28, v28, v182
	v_cndmask_b32_e64 v182, 0, v1, s[10:11]
	v_add_f32_e32 v29, v29, v182
	v_cndmask_b32_e64 v182, 0, v2, s[10:11]
	v_add_f32_e32 v30, v30, v182
	v_cndmask_b32_e64 v182, 0, v3, s[10:11]
	v_cndmask_b32_e64 v0, 0, v0, s[12:13]
	v_add_f32_e32 v31, v31, v182
	v_add_f32_e32 v182, v20, v0
	v_cndmask_b32_e64 v0, 0, v1, s[12:13]
	v_add_f32_e32 v183, v21, v0
	v_cndmask_b32_e64 v0, 0, v2, s[12:13]
	v_add_f32_e32 v200, v22, v0
	v_cndmask_b32_e64 v0, 0, v3, s[12:13]
	v_add_f32_e32 v214, v23, v0
	s_waitcnt vmcnt(23)
	v_pk_mul_f32 v[2:3], v[134:135], v[42:43]
	v_pk_mul_f32 v[0:1], v[132:133], v[40:41]
	s_waitcnt vmcnt(22)
	v_pk_mul_f32 v[22:23], v[138:139], v[38:39]
	v_pk_mul_f32 v[20:21], v[136:137], v[36:37]
	v_mfma_f32_16x16x32_bf16 v[0:3], v[16:19], v[206:209], v[0:3]
	ds_write2st64_b32 v205, v44, v45 offset1:1
	ds_write2st64_b32 v205, v46, v47 offset0:2 offset1:3
	ds_write2st64_b32 v205, v52, v53 offset0:4 offset1:5
	ds_write2st64_b32 v205, v54, v55 offset0:6 offset1:7
	ds_write2st64_b32 v205, v28, v29 offset0:8 offset1:9
	ds_write2st64_b32 v205, v30, v31 offset0:10 offset1:11
	ds_write2st64_b32 v205, v182, v183 offset0:12 offset1:13
	ds_write2st64_b32 v205, v200, v214 offset0:14 offset1:15
	v_lshlrev_b32_e32 v214, 2, v190
	v_add_u32_e32 v200, s33, v214
	v_mfma_f32_16x16x32_bf16 v[132:135], v[12:15], v[210:213], v[0:3]
	s_waitcnt lgkmcnt(0)
	s_barrier
	v_mfma_f32_16x16x32_bf16 v[0:3], v[4:7], v[206:209], v[20:23]
	v_lshl_add_u64 v[182:183], s[66:67], 0, v[180:181]
	s_mov_b32 s33, 0x15706000
	v_mfma_f32_16x16x32_bf16 v[136:139], v[8:11], v[210:213], v[0:3]
	s_nop 4
	ds_read2st64_b64 v[0:3], v200 offset1:8
	ds_read2st64_b64 v[220:223], v200 offset0:16 offset1:24
	ds_read2st64_b64 v[224:227], v200 offset0:32 offset1:40
	ds_read2st64_b64 v[228:231], v200 offset0:48 offset1:56
	s_waitcnt lgkmcnt(3)
	v_add_f32_e32 v0, 0, v0
	v_add_f32_e32 v1, 0, v1
	v_add_f32_e32 v4, v0, v2
	v_add_f32_e32 v5, v1, v3
	s_waitcnt lgkmcnt(2)
	v_add_f32_e32 v0, v4, v220
	v_add_f32_e32 v1, v5, v221
	v_add_f32_e32 v4, v0, v222
	v_add_f32_e32 v5, v1, v223
	s_waitcnt lgkmcnt(1)
	v_add_f32_e32 v0, v4, v224
	v_add_f32_e32 v1, v5, v225
	v_add_f32_e32 v4, v0, v226
	v_add_f32_e32 v5, v1, v227
	s_waitcnt lgkmcnt(0)
	v_add_f32_e32 v0, v4, v228
	v_add_f32_e32 v1, v5, v229
	v_add_f32_e32 v0, v0, v230
	v_add_f32_e32 v1, v1, v231
	v_cvt_pk_bf16_f32 v2, v0, v1
	v_add_co_u32_e32 v0, vcc, s84, v182
	s_nop 1
	v_addc_co_u32_e32 v1, vcc, 0, v183, vcc
	global_store_dword v[0:1], v2, off
	v_add_co_u32_e32 v0, vcc, s33, v188
	s_lshl_b32 s33, s18, 15
	s_nop 0
	v_addc_co_u32_e32 v1, vcc, 0, v189, vcc
	v_add_co_u32_e32 v4, vcc, s85, v184
	global_load_dwordx4 v[0:3], v[0:1], off
	s_nop 0
	v_addc_co_u32_e32 v5, vcc, 0, v185, vcc
	v_add_co_u32_e32 v8, vcc, s86, v184
	global_load_dwordx4 v[44:47], v[4:5], off
	global_load_dwordx4 v[52:55], v[4:5], off offset:1024
	global_load_dwordx4 v[28:31], v[4:5], off offset:2048
	global_load_dwordx4 v[20:23], v[4:5], off offset:3072
	v_addc_co_u32_e32 v9, vcc, 0, v185, vcc
	global_load_dwordx4 v[16:19], v[8:9], off
	global_load_dwordx4 v[12:15], v[8:9], off offset:1024
	global_load_dwordx4 v[4:7], v[8:9], off offset:2048
	s_nop 0
	global_load_dwordx4 v[8:11], v[8:9], off offset:3072
	s_nop 0
	global_load_dwordx4 v[40:43], v[186:187], off
	global_load_dwordx4 v[36:39], v[186:187], off offset:64
	s_lshl_b32 s18, s18, 11
	s_add_i32 s18, s69, s18
	v_add_u32_e32 v188, s18, v163
	ds_read_b64_tr_b16 v[184:185], v188
	v_add_u32_e32 v186, 0x80, v188
	ds_read_b64_tr_b16 v[186:187], v186
	v_add_u32_e32 v189, 0x400, v188
	ds_read_b64_tr_b16 v[206:207], v189
	v_add_u32_e32 v188, 0x480, v188
	ds_read_b64_tr_b16 v[208:209], v188
	s_waitcnt lgkmcnt(0)
	v_cvt_pk_bf16_f32 v210, v132, v133
	v_cvt_pk_bf16_f32 v211, v134, v135
	v_cvt_pk_bf16_f32 v212, v136, v137
	v_cvt_pk_bf16_f32 v213, v138, v139
	s_add_i32 s18, s33, 0
	s_waitcnt vmcnt(32)
	v_mfma_f32_16x16x32_bf16 v[72:75], v[72:75], v[210:213], 0
	s_add_i32 s33, s68, s18
	s_waitcnt vmcnt(31)
	v_mfma_f32_16x16x32_bf16 v[76:79], v[76:79], v[210:213], 0
	s_waitcnt vmcnt(30)
	v_mfma_f32_16x16x32_bf16 v[80:83], v[80:83], v[210:213], 0
	s_waitcnt vmcnt(29)
	v_mfma_f32_16x16x32_bf16 v[84:87], v[84:87], v[210:213], 0
	v_cndmask_b32_e64 v211, v207, v185, s[4:5]
	v_cndmask_b32_e64 v210, v206, v184, s[4:5]
	v_cndmask_b32_e64 v213, v209, v187, s[4:5]
	v_cndmask_b32_e64 v212, v208, v186, s[4:5]
	s_nop 1
	v_mfma_f32_16x16x32_bf16 v[60:63], v[60:63], v[210:213], 0
	s_nop 7
	v_cndmask_b32_e64 v188, 0, v60, s[6:7]
	v_add_f32_e32 v72, v72, v188
	v_cndmask_b32_e64 v188, 0, v61, s[6:7]
	v_add_f32_e32 v73, v73, v188
	v_cndmask_b32_e64 v188, 0, v62, s[6:7]
	v_add_f32_e32 v74, v74, v188
	v_cndmask_b32_e64 v188, 0, v63, s[6:7]
	v_add_f32_e32 v75, v75, v188
	v_cndmask_b32_e64 v188, 0, v60, s[8:9]
	v_add_f32_e32 v76, v76, v188
	v_cndmask_b32_e64 v188, 0, v61, s[8:9]
	v_add_f32_e32 v77, v77, v188
	v_cndmask_b32_e64 v188, 0, v62, s[8:9]
	v_add_f32_e32 v78, v78, v188
	v_cndmask_b32_e64 v188, 0, v63, s[8:9]
	v_add_f32_e32 v79, v79, v188
	v_cndmask_b32_e64 v188, 0, v60, s[10:11]
	v_cndmask_b32_e64 v60, 0, v60, s[12:13]
	v_add_f32_e32 v84, v84, v60
	v_cndmask_b32_e64 v60, 0, v61, s[12:13]
	v_add_f32_e32 v80, v80, v188
	v_cndmask_b32_e64 v188, 0, v61, s[10:11]
	v_add_f32_e32 v85, v85, v60
	v_cndmask_b32_e64 v60, 0, v62, s[12:13]
	v_add_f32_e32 v81, v81, v188
	v_cndmask_b32_e64 v188, 0, v62, s[10:11]
	v_add_f32_e32 v86, v86, v60
	v_cndmask_b32_e64 v60, 0, v63, s[12:13]
	v_add_f32_e32 v82, v82, v188
	v_cndmask_b32_e64 v188, 0, v63, s[10:11]
	v_add_f32_e32 v87, v87, v60
	s_waitcnt vmcnt(24)
	v_pk_mul_f32 v[62:63], v[66:67], v[134:135]
	v_pk_mul_f32 v[60:61], v[64:65], v[132:133]
	s_waitcnt vmcnt(23)
	v_pk_mul_f32 v[66:67], v[70:71], v[138:139]
	v_pk_mul_f32 v[64:65], v[68:69], v[136:137]
	v_add_f32_e32 v83, v83, v188
	v_mfma_f32_16x16x32_bf16 v[56:59], v[56:59], v[184:187], v[60:63]
	v_mfma_f32_16x16x32_bf16 v[24:27], v[24:27], v[184:187], v[64:67]
	v_mfma_f32_16x16x32_bf16 v[136:139], v[32:35], v[206:209], v[24:27]
	v_add_u32_e32 v32, s18, v214
	s_min_u32 s18, s96, 59
	s_nop 4
	v_add_u32_e32 v24, s33, v215
	ds_write2st64_b32 v24, v72, v73 offset1:1
	ds_write2st64_b32 v24, v74, v75 offset0:2 offset1:3
	ds_write2st64_b32 v24, v76, v77 offset0:4 offset1:5
	ds_write2st64_b32 v24, v78, v79 offset0:6 offset1:7
	ds_write2st64_b32 v24, v80, v81 offset0:8 offset1:9
	ds_write2st64_b32 v24, v82, v83 offset0:10 offset1:11
	ds_write2st64_b32 v24, v84, v85 offset0:12 offset1:13
	ds_write2st64_b32 v24, v86, v87 offset0:14 offset1:15
	s_waitcnt lgkmcnt(0)
	s_barrier
	ds_read2st64_b64 v[24:27], v32 offset1:8
	ds_read2st64_b64 v[220:223], v32 offset0:16 offset1:24
	ds_read2st64_b64 v[224:227], v32 offset0:32 offset1:40
	ds_read2st64_b64 v[228:231], v32 offset0:48 offset1:56
	s_add_i32 s33, s18, 4
	s_lshl_b32 s18, s33, 13
	v_mfma_f32_16x16x32_bf16 v[132:135], v[48:51], v[206:209], v[56:59]
	s_waitcnt lgkmcnt(3)
	v_add_f32_e32 v24, 0, v24
	v_add_f32_e32 v25, 0, v25
	v_add_f32_e32 v33, v24, v26
	v_add_f32_e32 v34, v25, v27
	s_waitcnt lgkmcnt(2)
	v_add_f32_e32 v24, v33, v220
	v_add_f32_e32 v25, v34, v221
	v_add_f32_e32 v33, v24, v222
	v_add_f32_e32 v34, v25, v223
	s_waitcnt lgkmcnt(1)
	v_add_f32_e32 v24, v33, v224
	v_add_f32_e32 v25, v34, v225
	v_add_f32_e32 v33, v24, v226
	v_add_f32_e32 v34, v25, v227
	s_waitcnt lgkmcnt(0)
	v_add_f32_e32 v24, v33, v228
	v_add_f32_e32 v25, v34, v229
	v_add_f32_e32 v24, v24, v230
	v_add_f32_e32 v25, v25, v231
	v_cvt_pk_bf16_f32 v26, v24, v25
	v_add_co_u32_e32 v24, vcc, s87, v182
	s_nop 1
	v_addc_co_u32_e32 v25, vcc, 0, v183, vcc
	global_store_dword v[24:25], v26, off
	v_lshl_add_u64 v[24:25], v[172:173], 0, s[18:19]
	s_lshl_b32 s18, s33, 15
	global_load_dwordx4 v[60:63], v[24:25], off
	v_lshl_add_u64 v[24:25], v[174:175], 0, s[18:19]
	v_lshl_add_u64 v[32:33], v[176:177], 0, s[18:19]
	global_load_dwordx4 v[72:75], v[24:25], off
	global_load_dwordx4 v[76:79], v[24:25], off offset:1024
	global_load_dwordx4 v[80:83], v[24:25], off offset:2048
	global_load_dwordx4 v[84:87], v[24:25], off offset:3072
	global_load_dwordx4 v[56:59], v[32:33], off
	global_load_dwordx4 v[48:51], v[32:33], off offset:1024
	s_nop 0
	global_load_dwordx4 v[24:27], v[32:33], off offset:2048
	s_nop 0
	global_load_dwordx4 v[32:35], v[32:33], off offset:3072
	s_lshl_b32 s18, s33, 10
	v_lshl_add_u64 v[68:69], v[178:179], 0, s[18:19]
	global_load_dwordx4 v[64:67], v[68:69], off
	s_nop 0
	global_load_dwordx4 v[68:71], v[68:69], off offset:64
	ds_read_b64_tr_b16 v[184:185], v201
	ds_read_b64_tr_b16 v[186:187], v202
	ds_read_b64_tr_b16 v[206:207], v203
	ds_read_b64_tr_b16 v[208:209], v204
	s_waitcnt lgkmcnt(0)
	v_cvt_pk_bf16_f32 v210, v132, v133
	v_cvt_pk_bf16_f32 v211, v134, v135
	v_cvt_pk_bf16_f32 v212, v136, v137
	v_cvt_pk_bf16_f32 v213, v138, v139
	s_waitcnt vmcnt(24)
	v_pk_mul_f32 v[106:107], v[106:107], v[138:139]
	v_mfma_f32_16x16x32_bf16 v[116:119], v[116:119], v[210:213], 0
	v_mul_f32_e64 v104, v104, v136
	v_mul_f32_e64 v105, v105, v137
	v_pk_mul_f32 v[110:111], v[110:111], v[134:135]
	v_pk_mul_f32 v[108:109], v[108:109], v[132:133]
	v_mfma_f32_16x16x32_bf16 v[120:123], v[120:123], v[210:213], 0
	s_mov_b64 s[54:55], 0x6000
	v_lshl_add_u64 v[180:181], v[180:181], 0, s[42:43]
	v_lshl_add_u64 v[166:167], v[166:167], 0, s[48:49]
	v_mfma_f32_16x16x32_bf16 v[124:127], v[124:127], v[210:213], 0
	v_lshl_add_u64 v[168:169], v[168:169], 0, s[50:51]
	v_lshl_add_u64 v[170:171], v[170:171], 0, s[54:55]
	s_cmp_lt_u32 s96, 60
	v_mfma_f32_16x16x32_bf16 v[128:131], v[128:131], v[210:213], 0
	v_cndmask_b32_e64 v211, v207, v185, s[4:5]
	v_cndmask_b32_e64 v210, v206, v184, s[4:5]
	v_cndmask_b32_e64 v213, v209, v187, s[4:5]
	v_cndmask_b32_e64 v212, v208, v186, s[4:5]
	v_mfma_f32_16x16x32_bf16 v[88:91], v[88:91], v[184:187], v[104:107]
	s_mov_b32 s18, s96
	v_mfma_f32_16x16x32_bf16 v[112:115], v[112:115], v[210:213], 0
	v_mfma_f32_16x16x32_bf16 v[136:139], v[92:95], v[206:209], v[88:91]
	v_mfma_f32_16x16x32_bf16 v[100:103], v[100:103], v[184:187], v[108:111]
	s_nop 5
	v_cndmask_b32_e64 v188, 0, v112, s[6:7]
	v_add_f32_e32 v116, v116, v188
	v_cndmask_b32_e64 v188, 0, v113, s[6:7]
	v_add_f32_e32 v117, v117, v188
	v_cndmask_b32_e64 v188, 0, v114, s[6:7]
	v_add_f32_e32 v118, v118, v188
	v_cndmask_b32_e64 v188, 0, v115, s[6:7]
	v_add_f32_e32 v119, v119, v188
	v_cndmask_b32_e64 v188, 0, v112, s[8:9]
	v_add_f32_e32 v120, v120, v188
	v_cndmask_b32_e64 v188, 0, v113, s[8:9]
	v_add_f32_e32 v121, v121, v188
	v_cndmask_b32_e64 v188, 0, v114, s[8:9]
	v_add_f32_e32 v122, v122, v188
	v_cndmask_b32_e64 v188, 0, v115, s[8:9]
	v_add_f32_e32 v123, v123, v188
	v_cndmask_b32_e64 v188, 0, v112, s[10:11]
	v_add_f32_e32 v124, v124, v188
	v_cndmask_b32_e64 v188, 0, v113, s[10:11]
	v_add_f32_e32 v125, v125, v188
	v_cndmask_b32_e64 v188, 0, v114, s[10:11]
	v_add_f32_e32 v126, v126, v188
	v_cndmask_b32_e64 v188, 0, v115, s[10:11]
	v_cndmask_b32_e64 v112, 0, v112, s[12:13]
	v_cndmask_b32_e64 v113, 0, v113, s[12:13]
	v_cndmask_b32_e64 v114, 0, v114, s[12:13]
	v_cndmask_b32_e64 v115, 0, v115, s[12:13]
	v_add_f32_e32 v127, v127, v188
	v_add_f32_e32 v112, v128, v112
	v_add_f32_e32 v113, v129, v113
	v_add_f32_e32 v114, v130, v114
	v_add_f32_e32 v115, v131, v115
	ds_write2st64_b32 v205, v116, v117 offset1:1
	ds_write2st64_b32 v205, v118, v119 offset0:2 offset1:3
	ds_write2st64_b32 v205, v120, v121 offset0:4 offset1:5
	ds_write2st64_b32 v205, v122, v123 offset0:6 offset1:7
	ds_write2st64_b32 v205, v124, v125 offset0:8 offset1:9
	ds_write2st64_b32 v205, v126, v127 offset0:10 offset1:11
	ds_write2st64_b32 v205, v112, v113 offset0:12 offset1:13
	ds_write2st64_b32 v205, v114, v115 offset0:14 offset1:15
	s_waitcnt lgkmcnt(0)
	s_barrier
	ds_read2st64_b64 v[88:91], v200 offset1:8
	ds_read2st64_b64 v[220:223], v200 offset0:16 offset1:24
	ds_read2st64_b64 v[224:227], v200 offset0:32 offset1:40
	ds_read2st64_b64 v[228:231], v200 offset0:48 offset1:56
	v_mfma_f32_16x16x32_bf16 v[132:135], v[96:99], v[206:209], v[100:103]
	s_waitcnt lgkmcnt(3)
	v_add_f32_e32 v88, 0, v88
	v_add_f32_e32 v89, 0, v89
	v_add_f32_e32 v92, v88, v90
	v_add_f32_e32 v93, v89, v91
	s_waitcnt lgkmcnt(2)
	v_add_f32_e32 v88, v92, v220
	v_add_f32_e32 v89, v93, v221
	v_add_f32_e32 v92, v88, v222
	v_add_f32_e32 v93, v89, v223
	s_waitcnt lgkmcnt(1)
	v_add_f32_e32 v88, v92, v224
	v_add_f32_e32 v89, v93, v225
	v_add_f32_e32 v92, v88, v226
	v_add_f32_e32 v93, v89, v227
	s_waitcnt lgkmcnt(0)
	v_add_f32_e32 v88, v92, v228
	v_add_f32_e32 v89, v93, v229
	v_add_f32_e32 v88, v88, v230
	v_add_f32_e32 v89, v89, v231
	v_cvt_pk_bf16_f32 v90, v88, v89
	v_add_co_u32_e32 v88, vcc, s88, v182
	s_nop 1
	v_addc_co_u32_e32 v89, vcc, 0, v183, vcc
	global_store_dword v[88:89], v90, off
	s_cbranch_scc1 .LBB0_457
	s_lshl_b32 s18, s93, 22
	s_and_b32 s18, s18, 0x1000000
	s_add_u32 s18, s66, s18
	s_addc_u32 s33, s67, 0
	s_lshl_b32 s54, s91, 10
	s_and_b32 s54, s54, 0xc00
	s_add_u32 s18, s18, s54
	s_waitcnt vmcnt(17)
	ds_read_b64_tr_b16 v[12:13], v191
	s_addc_u32 s33, s33, 0
	s_lshl_b32 s54, s91, 1
	ds_read_b64_tr_b16 v[14:15], v193
	s_and_b32 s54, s54, -16
	s_waitcnt vmcnt(4)
	ds_read_b64_tr_b16 v[24:25], v194
	s_ashr_i32 s55, s54, 31
	ds_read_b64_tr_b16 v[26:27], v195
	s_lshl_b64 s[54:55], s[54:55], 1
	s_waitcnt lgkmcnt(0)
	s_add_u32 s66, s18, s54
	s_addc_u32 s67, s33, s55
	v_cndmask_b32_e64 v13, v25, v13, s[4:5]
	v_cndmask_b32_e64 v12, v24, v12, s[4:5]
	v_cndmask_b32_e64 v15, v27, v15, s[4:5]
	v_cndmask_b32_e64 v14, v26, v14, s[4:5]
	v_cvt_pk_bf16_f32 v4, v132, v133
	v_cvt_pk_bf16_f32 v5, v134, v135
	v_cvt_pk_bf16_f32 v6, v136, v137
	v_cvt_pk_bf16_f32 v7, v138, v139
	s_nop 0
	v_mfma_f32_16x16x32_bf16 v[8:11], v[44:47], v[4:7], 0
	v_mfma_f32_16x16x32_bf16 v[0:3], v[0:3], v[12:15], 0
	v_mfma_f32_16x16x32_bf16 v[16:19], v[52:55], v[4:7], 0
	s_nop 6
	v_cndmask_b32_e64 v12, 0, v0, s[6:7]
	v_add_f32_e32 v8, v8, v12
	v_mfma_f32_16x16x32_bf16 v[12:15], v[28:31], v[4:7], 0
	v_cndmask_b32_e64 v24, 0, v1, s[6:7]
	v_add_f32_e32 v9, v9, v24
	v_cndmask_b32_e64 v24, 0, v2, s[6:7]
	v_mfma_f32_16x16x32_bf16 v[4:7], v[20:23], v[4:7], 0
	v_cndmask_b32_e64 v20, 0, v3, s[6:7]
	v_add_f32_e32 v11, v11, v20
	v_cndmask_b32_e64 v20, 0, v0, s[8:9]
	v_add_f32_e32 v16, v16, v20
	v_cndmask_b32_e64 v20, 0, v1, s[8:9]
	v_add_f32_e32 v17, v17, v20
	v_cndmask_b32_e64 v20, 0, v2, s[8:9]
	v_add_f32_e32 v18, v18, v20
	v_cndmask_b32_e64 v20, 0, v3, s[8:9]
	v_add_f32_e32 v19, v19, v20
	v_cndmask_b32_e64 v20, 0, v0, s[10:11]
	v_add_f32_e32 v12, v12, v20
	v_cndmask_b32_e64 v20, 0, v1, s[10:11]
	v_add_f32_e32 v13, v13, v20
	v_cndmask_b32_e64 v20, 0, v2, s[10:11]
	v_add_f32_e32 v14, v14, v20
	v_cndmask_b32_e64 v20, 0, v3, s[10:11]
	v_cndmask_b32_e64 v0, 0, v0, s[12:13]
	v_cndmask_b32_e64 v1, 0, v1, s[12:13]
	v_cndmask_b32_e64 v2, 0, v2, s[12:13]
	v_cndmask_b32_e64 v3, 0, v3, s[12:13]
	v_add_f32_e32 v0, v4, v0
	v_add_f32_e32 v1, v5, v1
	v_add_f32_e32 v2, v6, v2
	v_add_f32_e32 v3, v7, v3
	v_add_u32_e32 v4, s68, v196
	v_add_f32_e32 v10, v10, v24
	v_add_f32_e32 v15, v15, v20
	ds_write2st64_b32 v4, v8, v9 offset0:128 offset1:129
	ds_write2st64_b32 v4, v10, v11 offset0:130 offset1:131
	ds_write2st64_b32 v4, v16, v17 offset0:132 offset1:133
	ds_write2st64_b32 v4, v18, v19 offset0:134 offset1:135
	ds_write2st64_b32 v4, v12, v13 offset0:136 offset1:137
	ds_write2st64_b32 v4, v14, v15 offset0:138 offset1:139
	ds_write2st64_b32 v4, v0, v1 offset0:140 offset1:141
	ds_write2st64_b32 v4, v2, v3 offset0:142 offset1:143
	s_waitcnt lgkmcnt(0)
	s_barrier
	ds_read2st64_b64 v[0:3], v197 offset0:64 offset1:72
	ds_read2st64_b64 v[4:7], v197 offset0:80 offset1:88
	s_waitcnt lgkmcnt(1)
	v_add_f32_e32 v0, 0, v0
	v_add_f32_e32 v1, 0, v1
	v_add_f32_e32 v0, v0, v2
	v_add_f32_e32 v8, v1, v3
	s_waitcnt lgkmcnt(0)
	v_add_f32_e32 v4, v0, v4
	ds_read2st64_b64 v[0:3], v197 offset0:96 offset1:104
	v_add_f32_e32 v5, v8, v5
	v_add_f32_e32 v8, v4, v6
	v_add_f32_e32 v9, v5, v7
	ds_read2st64_b64 v[4:7], v197 offset0:112 offset1:120
	s_waitcnt lgkmcnt(1)
	v_add_f32_e32 v0, v8, v0
	v_add_f32_e32 v1, v9, v1
	v_add_f32_e32 v0, v0, v2
	v_add_f32_e32 v1, v1, v3
	s_waitcnt lgkmcnt(0)
	v_add_f32_e32 v0, v0, v4
	v_add_f32_e32 v1, v1, v5
	v_add_f32_e32 v0, v0, v6
	v_add_f32_e32 v1, v1, v7
	v_cvt_pk_bf16_f32 v4, v0, v1
	v_lshl_add_u64 v[0:1], s[66:67], 0, v[146:147]
	v_lshlrev_b32_e32 v2, 1, v148
	v_mov_b32_e32 v3, v143
	v_lshl_add_u64 v[0:1], v[0:1], 0, v[2:3]
	v_add_co_u32_e32 v0, vcc, 0x1a7c0000, v0
	s_mov_b64 s[66:67], 0
	s_nop 0
	v_addc_co_u32_e32 v1, vcc, 0, v1, vcc
	global_store_dword v[0:1], v4, off
	s_barrier

.LBB0_589:
	ds_read_b128 v[144:147], v153
	ds_read_b128 v[158:161], v153 offset:1024
	ds_read_b128 v[162:165], v153 offset:2048
	ds_read_b128 v[166:169], v153 offset:3072
	ds_read_b128 v[170:173], v154
	ds_read_b128 v[174:177], v154 offset:1024
	ds_read_b128 v[178:181], v154 offset:2048
	ds_read_b128 v[182:185], v154 offset:3072
	s_add_u32 s33, s48, 0xfff80080
	s_addc_u32 s50, s49, -1
	s_cmp_eq_u32 s77, 28
	s_cselect_b32 s59, s35, s50
	s_cselect_b32 s58, s41, s33
	s_cselect_b32 s51, s31, s75
	s_cselect_b32 s50, s73, s74
	v_lshl_add_u64 v[148:149], s[48:49], 0, v[136:137]
	s_add_i32 m0, s43, 0xc000
	ds_read_b128 v[186:189], v155
	ds_read_b128 v[194:197], v155 offset:1024
	ds_read_b128 v[198:201], v155 offset:2048
	ds_read_b128 v[202:205], v155 offset:3072
	ds_read_b128 v[206:209], v155 offset:4096
	ds_read_b128 v[210:213], v155 offset:5120
	ds_read_b128 v[214:217], v155 offset:6144
	ds_read_b128 v[218:221], v155 offset:7168
	global_load_lds_dwordx4 v[148:149], off
	v_lshl_add_u64 v[148:149], s[48:49], 0, v[138:139]
	s_add_i32 m0, s43, 0xe000
	s_nop 0
	global_load_lds_dwordx4 v[148:149], off
	s_waitcnt vmcnt(8)
	s_waitcnt lgkmcnt(0)
	s_barrier
	s_waitcnt lgkmcnt(0)
	v_mfma_f32_16x16x32_bf16 v[124:127], v[144:147], v[186:189], v[124:127]
	v_mfma_f32_16x16x32_bf16 v[120:123], v[162:165], v[186:189], v[120:123]
	v_mfma_f32_16x16x32_bf16 v[108:111], v[144:147], v[198:201], v[108:111]
	v_mfma_f32_16x16x32_bf16 v[104:107], v[162:165], v[198:201], v[104:107]
	v_mfma_f32_16x16x32_bf16 v[92:95], v[144:147], v[206:209], v[92:95]
	v_mfma_f32_16x16x32_bf16 v[88:91], v[162:165], v[206:209], v[88:91]
	v_mfma_f32_16x16x32_bf16 v[76:79], v[144:147], v[214:217], v[76:79]
	v_mfma_f32_16x16x32_bf16 v[72:75], v[162:165], v[214:217], v[72:75]
	v_mfma_f32_16x16x32_bf16 v[124:127], v[158:161], v[194:197], v[124:127]
	v_mfma_f32_16x16x32_bf16 v[120:123], v[166:169], v[194:197], v[120:123]
	v_mfma_f32_16x16x32_bf16 v[108:111], v[158:161], v[202:205], v[108:111]
	v_mfma_f32_16x16x32_bf16 v[104:107], v[166:169], v[202:205], v[104:107]
	v_mfma_f32_16x16x32_bf16 v[92:95], v[158:161], v[210:213], v[92:95]
	v_mfma_f32_16x16x32_bf16 v[88:91], v[166:169], v[210:213], v[88:91]
	v_mfma_f32_16x16x32_bf16 v[76:79], v[158:161], v[218:221], v[76:79]
	v_mfma_f32_16x16x32_bf16 v[72:75], v[166:169], v[218:221], v[72:75]
	v_mfma_f32_16x16x32_bf16 v[116:119], v[170:173], v[186:189], v[116:119]
	v_mfma_f32_16x16x32_bf16 v[112:115], v[178:181], v[186:189], v[112:115]
	v_mfma_f32_16x16x32_bf16 v[100:103], v[170:173], v[198:201], v[100:103]
	v_mfma_f32_16x16x32_bf16 v[96:99], v[178:181], v[198:201], v[96:99]
	v_mfma_f32_16x16x32_bf16 v[84:87], v[170:173], v[206:209], v[84:87]
	v_mfma_f32_16x16x32_bf16 v[80:83], v[178:181], v[206:209], v[80:83]
	v_mfma_f32_16x16x32_bf16 v[68:71], v[170:173], v[214:217], v[68:71]
	v_mfma_f32_16x16x32_bf16 v[64:67], v[178:181], v[214:217], v[64:67]
	v_mfma_f32_16x16x32_bf16 v[116:119], v[174:177], v[194:197], v[116:119]
	v_mfma_f32_16x16x32_bf16 v[112:115], v[182:185], v[194:197], v[112:115]
	v_mfma_f32_16x16x32_bf16 v[100:103], v[174:177], v[202:205], v[100:103]
	v_mfma_f32_16x16x32_bf16 v[96:99], v[182:185], v[202:205], v[96:99]
	v_mfma_f32_16x16x32_bf16 v[84:87], v[174:177], v[210:213], v[84:87]
	v_mfma_f32_16x16x32_bf16 v[80:83], v[182:185], v[210:213], v[80:83]
	v_mfma_f32_16x16x32_bf16 v[68:71], v[174:177], v[218:221], v[68:71]
	v_mfma_f32_16x16x32_bf16 v[64:67], v[182:185], v[218:221], v[64:67]
	s_barrier
	s_add_i32 s33, s71, s64
	v_lshl_add_u64 v[148:149], s[50:51], 0, v[130:131]
	s_mov_b32 m0, s33
	ds_read_b128 v[186:189], v155 offset:16384
	ds_read_b128 v[194:197], v155 offset:17408
	ds_read_b128 v[198:201], v155 offset:18432
	ds_read_b128 v[202:205], v155 offset:19456
	ds_read_b128 v[206:209], v155 offset:20480
	ds_read_b128 v[210:213], v155 offset:21504
	ds_read_b128 v[214:217], v155 offset:22528
	ds_read_b128 v[218:221], v155 offset:23552
	global_load_lds_dwordx4 v[148:149], off
	s_add_i32 m0, s33, 0x2000
	s_add_u32 s54, s50, 0x80000
	v_lshl_add_u64 v[190:191], s[50:51], 0, v[134:135]
	s_addc_u32 s55, s51, 0
	s_add_i32 s33, s72, s64
	global_load_lds_dwordx4 v[190:191], off
	v_lshl_add_u64 v[222:223], s[54:55], 0, v[130:131]
	s_mov_b32 m0, s33
	v_lshl_add_u64 v[224:225], s[58:59], 0, v[132:133]
	global_load_lds_dwordx4 v[222:223], off
	v_lshl_add_u64 v[222:223], s[54:55], 0, v[134:135]
	s_add_i32 m0, s33, 0x2000
	s_nop 0
	global_load_lds_dwordx4 v[222:223], off
	v_lshl_add_u64 v[222:223], s[58:59], 0, v[128:129]
	s_mov_b32 m0, s43
	s_nop 0
	global_load_lds_dwordx4 v[222:223], off
	s_mov_b32 m0, s65
	s_nop 0
	global_load_lds_dwordx4 v[224:225], off
	s_waitcnt vmcnt(8)
	s_waitcnt lgkmcnt(0)
	s_barrier
	s_waitcnt lgkmcnt(0)
	v_mfma_f32_16x16x32_bf16 v[60:63], v[144:147], v[186:189], v[60:63]
	v_mfma_f32_16x16x32_bf16 v[56:59], v[162:165], v[186:189], v[56:59]
	v_mfma_f32_16x16x32_bf16 v[44:47], v[144:147], v[198:201], v[44:47]
	v_mfma_f32_16x16x32_bf16 v[40:43], v[162:165], v[198:201], v[40:43]
	v_mfma_f32_16x16x32_bf16 v[28:31], v[144:147], v[206:209], v[28:31]
	v_mfma_f32_16x16x32_bf16 v[24:27], v[162:165], v[206:209], v[24:27]
	v_mfma_f32_16x16x32_bf16 v[12:15], v[144:147], v[214:217], v[12:15]
	v_mfma_f32_16x16x32_bf16 v[8:11], v[162:165], v[214:217], v[8:11]
	v_mfma_f32_16x16x32_bf16 v[60:63], v[158:161], v[194:197], v[60:63]
	v_mfma_f32_16x16x32_bf16 v[56:59], v[166:169], v[194:197], v[56:59]
	v_mfma_f32_16x16x32_bf16 v[44:47], v[158:161], v[202:205], v[44:47]
	v_mfma_f32_16x16x32_bf16 v[40:43], v[166:169], v[202:205], v[40:43]
	v_mfma_f32_16x16x32_bf16 v[28:31], v[158:161], v[210:213], v[28:31]
	v_mfma_f32_16x16x32_bf16 v[24:27], v[166:169], v[210:213], v[24:27]
	v_mfma_f32_16x16x32_bf16 v[12:15], v[158:161], v[218:221], v[12:15]
	v_mfma_f32_16x16x32_bf16 v[8:11], v[166:169], v[218:221], v[8:11]
	v_mfma_f32_16x16x32_bf16 v[52:55], v[170:173], v[186:189], v[52:55]
	v_mfma_f32_16x16x32_bf16 v[48:51], v[178:181], v[186:189], v[48:51]
	v_mfma_f32_16x16x32_bf16 v[36:39], v[170:173], v[198:201], v[36:39]
	v_mfma_f32_16x16x32_bf16 v[32:35], v[178:181], v[198:201], v[32:35]
	v_mfma_f32_16x16x32_bf16 v[20:23], v[170:173], v[206:209], v[20:23]
	v_mfma_f32_16x16x32_bf16 v[16:19], v[178:181], v[206:209], v[16:19]
	v_mfma_f32_16x16x32_bf16 v[4:7], v[170:173], v[214:217], v[4:7]
	v_mfma_f32_16x16x32_bf16 v[0:3], v[178:181], v[214:217], v[0:3]
	v_mfma_f32_16x16x32_bf16 v[52:55], v[174:177], v[194:197], v[52:55]
	v_mfma_f32_16x16x32_bf16 v[48:51], v[182:185], v[194:197], v[48:51]
	v_mfma_f32_16x16x32_bf16 v[36:39], v[174:177], v[202:205], v[36:39]
	v_mfma_f32_16x16x32_bf16 v[32:35], v[182:185], v[202:205], v[32:35]
	v_mfma_f32_16x16x32_bf16 v[20:23], v[174:177], v[210:213], v[20:23]
	v_mfma_f32_16x16x32_bf16 v[16:19], v[182:185], v[210:213], v[16:19]
	v_mfma_f32_16x16x32_bf16 v[4:7], v[174:177], v[218:221], v[4:7]
	v_mfma_f32_16x16x32_bf16 v[0:3], v[182:185], v[218:221], v[0:3]
	s_barrier
	s_add_i32 s33, 0, 0x18000
	v_add_u32_e32 v157, s33, v151
	s_add_i32 s56, 0, 0x1c000
	ds_read_b128 v[144:147], v157
	ds_read_b128 v[158:161], v157 offset:1024
	ds_read_b128 v[162:165], v157 offset:2048
	ds_read_b128 v[166:169], v157 offset:3072
	v_add_u32_e32 v157, s56, v151
	ds_read_b128 v[170:173], v157
	ds_read_b128 v[174:177], v157 offset:1024
	ds_read_b128 v[178:181], v157 offset:2048
	ds_read_b128 v[182:185], v157 offset:3072
	s_add_u32 s54, s58, 0x80000
	s_addc_u32 s55, s59, 0
	s_mov_b32 m0, s66
	v_lshl_add_u64 v[226:227], s[54:55], 0, v[128:129]
	ds_read_b128 v[186:189], v155 offset:32768
	ds_read_b128 v[194:197], v155 offset:33792
	ds_read_b128 v[198:201], v155 offset:34816
	ds_read_b128 v[202:205], v155 offset:35840
	ds_read_b128 v[206:209], v155 offset:36864
	ds_read_b128 v[210:213], v155 offset:37888
	ds_read_b128 v[214:217], v155 offset:38912
	ds_read_b128 v[218:221], v155 offset:39936
	global_load_lds_dwordx4 v[226:227], off
	v_lshl_add_u64 v[226:227], s[54:55], 0, v[132:133]
	s_mov_b32 m0, s67
	s_nop 0
	global_load_lds_dwordx4 v[226:227], off
	s_waitcnt vmcnt(8)
	s_waitcnt lgkmcnt(0)
	s_barrier
	s_waitcnt lgkmcnt(0)
	v_mfma_f32_16x16x32_bf16 v[124:127], v[144:147], v[186:189], v[124:127]
	v_mfma_f32_16x16x32_bf16 v[120:123], v[162:165], v[186:189], v[120:123]
	v_mfma_f32_16x16x32_bf16 v[108:111], v[144:147], v[198:201], v[108:111]
	v_mfma_f32_16x16x32_bf16 v[104:107], v[162:165], v[198:201], v[104:107]
	v_mfma_f32_16x16x32_bf16 v[92:95], v[144:147], v[206:209], v[92:95]
	v_mfma_f32_16x16x32_bf16 v[88:91], v[162:165], v[206:209], v[88:91]
	v_mfma_f32_16x16x32_bf16 v[76:79], v[144:147], v[214:217], v[76:79]
	v_mfma_f32_16x16x32_bf16 v[72:75], v[162:165], v[214:217], v[72:75]
	v_mfma_f32_16x16x32_bf16 v[124:127], v[158:161], v[194:197], v[124:127]
	v_mfma_f32_16x16x32_bf16 v[120:123], v[166:169], v[194:197], v[120:123]
	v_mfma_f32_16x16x32_bf16 v[108:111], v[158:161], v[202:205], v[108:111]
	v_mfma_f32_16x16x32_bf16 v[104:107], v[166:169], v[202:205], v[104:107]
	v_mfma_f32_16x16x32_bf16 v[92:95], v[158:161], v[210:213], v[92:95]
	v_mfma_f32_16x16x32_bf16 v[88:91], v[166:169], v[210:213], v[88:91]
	v_mfma_f32_16x16x32_bf16 v[76:79], v[158:161], v[218:221], v[76:79]
	v_mfma_f32_16x16x32_bf16 v[72:75], v[166:169], v[218:221], v[72:75]
	v_mfma_f32_16x16x32_bf16 v[116:119], v[170:173], v[186:189], v[116:119]
	v_mfma_f32_16x16x32_bf16 v[112:115], v[178:181], v[186:189], v[112:115]
	v_mfma_f32_16x16x32_bf16 v[100:103], v[170:173], v[198:201], v[100:103]
	v_mfma_f32_16x16x32_bf16 v[96:99], v[178:181], v[198:201], v[96:99]
	v_mfma_f32_16x16x32_bf16 v[84:87], v[170:173], v[206:209], v[84:87]
	v_mfma_f32_16x16x32_bf16 v[80:83], v[178:181], v[206:209], v[80:83]
	v_mfma_f32_16x16x32_bf16 v[68:71], v[170:173], v[214:217], v[68:71]
	v_mfma_f32_16x16x32_bf16 v[64:67], v[178:181], v[214:217], v[64:67]
	v_mfma_f32_16x16x32_bf16 v[116:119], v[174:177], v[194:197], v[116:119]
	v_mfma_f32_16x16x32_bf16 v[112:115], v[182:185], v[194:197], v[112:115]
	v_mfma_f32_16x16x32_bf16 v[100:103], v[174:177], v[202:205], v[100:103]
	v_mfma_f32_16x16x32_bf16 v[96:99], v[182:185], v[202:205], v[96:99]
	v_mfma_f32_16x16x32_bf16 v[84:87], v[174:177], v[210:213], v[84:87]
	v_mfma_f32_16x16x32_bf16 v[80:83], v[182:185], v[210:213], v[80:83]
	v_mfma_f32_16x16x32_bf16 v[68:71], v[174:177], v[218:221], v[68:71]
	v_mfma_f32_16x16x32_bf16 v[64:67], v[182:185], v[218:221], v[64:67]
	s_barrier
	s_add_i32 s33, s33, s64
	v_lshl_add_u64 v[148:149], v[148:149], 0, s[18:19]
	s_mov_b32 m0, s33
	ds_read_b128 v[186:189], v155 offset:49152
	ds_read_b128 v[194:197], v155 offset:50176
	ds_read_b128 v[198:201], v155 offset:51200
	ds_read_b128 v[202:205], v155 offset:52224
	ds_read_b128 v[206:209], v155 offset:53248
	ds_read_b128 v[210:213], v155 offset:54272
	ds_read_b128 v[214:217], v155 offset:55296
	ds_read_b128 v[218:221], v155 offset:56320
	global_load_lds_dwordx4 v[148:149], off
	s_add_i32 m0, s33, 0x2000
	s_add_u32 s50, s50, 0x80080
	v_lshl_add_u64 v[148:149], v[190:191], 0, s[18:19]
	s_addc_u32 s51, s51, 0
	s_add_i32 s33, s56, s64
	global_load_lds_dwordx4 v[148:149], off
	v_lshl_add_u64 v[148:149], s[50:51], 0, v[130:131]
	s_mov_b32 m0, s33
	s_nop 0
	global_load_lds_dwordx4 v[148:149], off
	v_lshl_add_u64 v[148:149], s[50:51], 0, v[134:135]
	s_add_i32 m0, s33, 0x2000
	s_nop 0
	global_load_lds_dwordx4 v[148:149], off
	v_lshl_add_u64 v[148:149], v[222:223], 0, s[18:19]
	s_mov_b32 m0, s69
	s_nop 0
	global_load_lds_dwordx4 v[148:149], off
	v_lshl_add_u64 v[148:149], v[224:225], 0, s[18:19]
	s_mov_b32 m0, s70
	s_nop 0
	global_load_lds_dwordx4 v[148:149], off
	s_waitcnt vmcnt(8)
	s_waitcnt lgkmcnt(0)
	s_barrier
	s_waitcnt lgkmcnt(0)
	v_mfma_f32_16x16x32_bf16 v[60:63], v[144:147], v[186:189], v[60:63]
	v_mfma_f32_16x16x32_bf16 v[56:59], v[162:165], v[186:189], v[56:59]
	v_mfma_f32_16x16x32_bf16 v[44:47], v[144:147], v[198:201], v[44:47]
	v_mfma_f32_16x16x32_bf16 v[40:43], v[162:165], v[198:201], v[40:43]
	v_mfma_f32_16x16x32_bf16 v[28:31], v[144:147], v[206:209], v[28:31]
	v_mfma_f32_16x16x32_bf16 v[24:27], v[162:165], v[206:209], v[24:27]
	v_mfma_f32_16x16x32_bf16 v[12:15], v[144:147], v[214:217], v[12:15]
	v_mfma_f32_16x16x32_bf16 v[8:11], v[162:165], v[214:217], v[8:11]
	v_mfma_f32_16x16x32_bf16 v[60:63], v[158:161], v[194:197], v[60:63]
	v_mfma_f32_16x16x32_bf16 v[56:59], v[166:169], v[194:197], v[56:59]
	v_mfma_f32_16x16x32_bf16 v[44:47], v[158:161], v[202:205], v[44:47]
	v_mfma_f32_16x16x32_bf16 v[40:43], v[166:169], v[202:205], v[40:43]
	v_mfma_f32_16x16x32_bf16 v[28:31], v[158:161], v[210:213], v[28:31]
	v_mfma_f32_16x16x32_bf16 v[24:27], v[166:169], v[210:213], v[24:27]
	v_mfma_f32_16x16x32_bf16 v[12:15], v[158:161], v[218:221], v[12:15]
	v_mfma_f32_16x16x32_bf16 v[8:11], v[166:169], v[218:221], v[8:11]
	v_mfma_f32_16x16x32_bf16 v[52:55], v[170:173], v[186:189], v[52:55]
	v_mfma_f32_16x16x32_bf16 v[48:51], v[178:181], v[186:189], v[48:51]
	v_mfma_f32_16x16x32_bf16 v[36:39], v[170:173], v[198:201], v[36:39]
	v_mfma_f32_16x16x32_bf16 v[32:35], v[178:181], v[198:201], v[32:35]
	v_mfma_f32_16x16x32_bf16 v[20:23], v[170:173], v[206:209], v[20:23]
	v_mfma_f32_16x16x32_bf16 v[16:19], v[178:181], v[206:209], v[16:19]
	v_mfma_f32_16x16x32_bf16 v[4:7], v[170:173], v[214:217], v[4:7]
	v_mfma_f32_16x16x32_bf16 v[0:3], v[178:181], v[214:217], v[0:3]
	v_mfma_f32_16x16x32_bf16 v[52:55], v[174:177], v[194:197], v[52:55]
	v_mfma_f32_16x16x32_bf16 v[48:51], v[182:185], v[194:197], v[48:51]
	v_mfma_f32_16x16x32_bf16 v[36:39], v[174:177], v[202:205], v[36:39]
	v_mfma_f32_16x16x32_bf16 v[32:35], v[182:185], v[202:205], v[32:35]
	v_mfma_f32_16x16x32_bf16 v[20:23], v[174:177], v[210:213], v[20:23]
	v_mfma_f32_16x16x32_bf16 v[16:19], v[182:185], v[210:213], v[16:19]
	v_mfma_f32_16x16x32_bf16 v[4:7], v[174:177], v[218:221], v[4:7]
	v_mfma_f32_16x16x32_bf16 v[0:3], v[182:185], v[218:221], v[0:3]
	s_barrier
	s_add_i32 s77, s77, 2
	s_add_u32 s48, s48, 0x100
	s_addc_u32 s49, s49, 0
	s_add_u32 s74, s74, 0x100
	s_addc_u32 s75, s75, 0
	s_cmp_gt_u32 s77, 29
	s_cbranch_scc0 .LBB0_589
	v_lshl_add_u32 v148, s40, 8, v150
	v_lshl_or_b32 v146, s42, 8, v152
	v_ashrrev_i32_e32 v149, 31, v148
	v_ashrrev_i32_e32 v147, 31, v146
	v_lshlrev_b64 v[144:145], 11, v[148:149]
	v_lshl_add_u64 v[144:145], v[144:145], 0, v[146:147]
	v_lshl_add_u64 v[166:167], v[144:145], 2, s[10:11]
	v_mov_b32_e32 v244, v166
	v_mov_b32_e32 v245, v167
	global_load_dwordx4 v[172:175], v[244:245], off nt
	global_load_dwordx4 v[176:179], v[244:245], off offset:16 nt
	global_load_dwordx4 v[180:183], v[244:245], off offset:512 nt
	global_load_dwordx4 v[184:187], v[244:245], off offset:528 nt
	v_add_co_u32_e32 v240, vcc, 0x20000, v244
	s_nop 1
	v_addc_co_u32_e32 v241, vcc, 0, v245, vcc
	global_load_dwordx4 v[188:191], v[240:241], off nt
	global_load_dwordx4 v[196:199], v[240:241], off offset:16 nt
	global_load_dwordx4 v[200:203], v[240:241], off offset:512 nt
	global_load_dwordx4 v[204:207], v[240:241], off offset:528 nt
	v_add_co_u32_e32 v242, vcc, 0x40000, v244
	s_nop 1
	v_addc_co_u32_e32 v243, vcc, 0, v245, vcc
	global_load_dwordx4 v[208:211], v[242:243], off nt
	global_load_dwordx4 v[212:215], v[242:243], off offset:16 nt
	global_load_dwordx4 v[216:219], v[242:243], off offset:512 nt
	global_load_dwordx4 v[220:223], v[242:243], off offset:528 nt
	v_add_co_u32_e32 v240, vcc, 0x60000, v244
	s_nop 1
	v_addc_co_u32_e32 v241, vcc, 0, v245, vcc
	global_load_dwordx4 v[224:227], v[240:241], off nt
	global_load_dwordx4 v[228:231], v[240:241], off offset:16 nt
	global_load_dwordx4 v[232:235], v[240:241], off offset:512 nt
	global_load_dwordx4 v[236:239], v[240:241], off offset:528 nt
	s_and_b64 vcc, exec, s[20:21]
	s_cbranch_vccz .LBB0_592
	s_barrier
.LBB0_592:
	s_waitcnt vmcnt(15)
	s_nop 0
	v_mov_b32_e32 v158, v172
	v_mov_b32_e32 v159, v173
	v_mov_b32_e32 v160, v174
	v_mov_b32_e32 v161, v175
	s_waitcnt vmcnt(14)
	s_nop 0
	v_mov_b32_e32 v162, v176
	v_mov_b32_e32 v163, v177
	v_mov_b32_e32 v164, v178
	v_mov_b32_e32 v165, v179
	v_lshl_add_u64 v[168:169], v[144:145], 1, s[14:15]
	v_xor_b32_e32 v157, 32, v156
	v_pk_add_f32 v[126:127], v[126:127], v[160:161]
	v_pk_add_f32 v[170:171], v[124:125], v[158:159]
	v_pk_add_f32 v[164:165], v[122:123], v[164:165]
	v_pk_add_f32 v[162:163], v[120:121], v[162:163]
	v_cvt_pk_bf16_f32 v120, v170, v171
	v_cvt_pk_bf16_f32 v121, v126, v127
	v_mul_f32_e32 v127, v127, v127
	v_cvt_pk_bf16_f32 v122, v162, v163
	v_cvt_pk_bf16_f32 v123, v164, v165
	global_store_dwordx4 v[168:169], v[120:123], off
	s_waitcnt vmcnt(13)
	s_nop 0
	v_mov_b32_e32 v122, v180
	v_mov_b32_e32 v123, v181
	v_mov_b32_e32 v124, v182
	v_mov_b32_e32 v125, v183
	s_nop 0
	s_waitcnt vmcnt(12)
	s_nop 0
	v_mov_b32_e32 v158, v184
	v_mov_b32_e32 v159, v185
	v_mov_b32_e32 v160, v186
	v_mov_b32_e32 v161, v187
	v_mul_f32_e32 v166, v171, v171
	v_mul_f32_e32 v163, v163, v163
	v_fmac_f32_e32 v166, v170, v170
	v_fmac_f32_e32 v127, v126, v126
	v_mul_f32_e32 v165, v165, v165
	v_fmac_f32_e32 v163, v162, v162
	v_add_f32_e32 v126, v166, v127
	v_fmac_f32_e32 v165, v164, v164
	v_add_f32_e32 v126, v126, v163
	v_add_f32_e32 v162, v165, v126
	v_and_b32_e32 v121, 64, v156
	v_xor_b32_e32 v120, 16, v156
	v_add_u32_e32 v121, 64, v121
	v_cmp_lt_i32_e32 vcc, v120, v121
	v_pk_add_f32 v[118:119], v[118:119], v[124:125]
	v_pk_add_f32 v[116:117], v[116:117], v[122:123]
	v_pk_add_f32 v[126:127], v[114:115], v[160:161]
	v_pk_add_f32 v[112:113], v[112:113], v[158:159]
	v_mul_f32_e32 v114, v117, v117
	v_mul_f32_e32 v115, v119, v119
	v_mul_f32_e32 v122, v113, v113
	v_fmac_f32_e32 v114, v116, v116
	v_fmac_f32_e32 v115, v118, v118
	v_mul_f32_e32 v123, v127, v127
	v_fmac_f32_e32 v122, v112, v112
	v_add_f32_e32 v114, v114, v115
	v_fmac_f32_e32 v123, v126, v126
	v_add_f32_e32 v114, v114, v122
	v_cndmask_b32_e32 v120, v156, v120, vcc
	v_add_f32_e32 v114, v123, v114
	v_lshlrev_b32_e32 v120, 2, v120
	v_add_f32_e32 v114, v162, v114
	ds_bpermute_b32 v115, v120, v114
	v_cmp_lt_i32_e32 vcc, v157, v121
	v_cvt_pk_bf16_f32 v122, v116, v117
	v_cvt_pk_bf16_f32 v123, v118, v119
	v_cvt_pk_bf16_f32 v124, v112, v113
	s_waitcnt lgkmcnt(0)
	v_add_f32_e32 v115, v114, v115
	v_lshl_add_u64 v[112:113], v[148:149], 2, s[16:17]
	v_cndmask_b32_e32 v121, v156, v157, vcc
	v_lshlrev_b32_e32 v114, 2, v121
	ds_bpermute_b32 v116, v114, v115
	v_cvt_pk_bf16_f32 v125, v126, v127
	global_store_dwordx4 v[168:169], v[122:125], off offset:256
	s_and_saveexec_b64 s[40:41], s[6:7]
	s_cbranch_execz .LBB0_594
	s_waitcnt lgkmcnt(0)
	v_add_f32_e32 v115, v115, v116
	global_atomic_add_f32 v[112:113], v115, off
.LBB0_594:
	s_or_b64 exec, exec, s[40:41]
	s_waitcnt lgkmcnt(0)
	v_or_b32_e32 v116, 16, v148
	v_ashrrev_i32_e32 v117, 31, v116
	v_lshlrev_b64 v[116:117], 11, v[116:117]
	v_lshl_add_u64 v[126:127], v[116:117], 0, v[146:147]
	v_lshl_add_u64 v[158:159], v[126:127], 2, s[10:11]
	s_waitcnt vmcnt(11)
	s_nop 0
	v_mov_b32_e32 v116, v188
	v_mov_b32_e32 v117, v189
	v_mov_b32_e32 v118, v190
	v_mov_b32_e32 v119, v191
	s_waitcnt vmcnt(10)
	s_nop 0
	v_mov_b32_e32 v122, v196
	v_mov_b32_e32 v123, v197
	v_mov_b32_e32 v124, v198
	v_mov_b32_e32 v125, v199
	v_lshl_add_u64 v[126:127], v[126:127], 1, s[14:15]
	v_pk_add_f32 v[118:119], v[110:111], v[118:119]
	v_pk_add_f32 v[116:117], v[108:109], v[116:117]
	v_pk_add_f32 v[124:125], v[106:107], v[124:125]
	v_pk_add_f32 v[122:123], v[104:105], v[122:123]
	v_cvt_pk_bf16_f32 v104, v116, v117
	v_cvt_pk_bf16_f32 v105, v118, v119
	v_mul_f32_e32 v115, v117, v117
	v_cvt_pk_bf16_f32 v106, v122, v123
	v_cvt_pk_bf16_f32 v107, v124, v125
	global_store_dwordx4 v[126:127], v[104:107], off
	s_waitcnt vmcnt(9)
	s_nop 0
	v_mov_b32_e32 v104, v200
	v_mov_b32_e32 v105, v201
	v_mov_b32_e32 v106, v202
	v_mov_b32_e32 v107, v203
	s_nop 0
	s_waitcnt vmcnt(8)
	s_nop 0
	v_mov_b32_e32 v108, v204
	v_mov_b32_e32 v109, v205
	v_mov_b32_e32 v110, v206
	v_mov_b32_e32 v111, v207
	v_mul_f32_e32 v117, v119, v119
	v_mul_f32_e32 v119, v123, v123
	v_fmac_f32_e32 v115, v116, v116
	v_fmac_f32_e32 v117, v118, v118
	v_mul_f32_e32 v121, v125, v125
	v_fmac_f32_e32 v119, v122, v122
	v_add_f32_e32 v115, v115, v117
	v_fmac_f32_e32 v121, v124, v124
	v_add_f32_e32 v115, v115, v119
	v_add_f32_e32 v115, v121, v115
	v_pk_add_f32 v[102:103], v[102:103], v[106:107]
	v_pk_add_f32 v[100:101], v[100:101], v[104:105]
	v_pk_add_f32 v[106:107], v[96:97], v[108:109]
	v_mul_f32_e32 v96, v101, v101
	v_mul_f32_e32 v97, v103, v103
	v_pk_add_f32 v[104:105], v[98:99], v[110:111]
	v_mul_f32_e32 v98, v107, v107
	v_fmac_f32_e32 v96, v100, v100
	v_fmac_f32_e32 v97, v102, v102
	v_mul_f32_e32 v99, v105, v105
	v_fmac_f32_e32 v98, v106, v106
	v_add_f32_e32 v96, v96, v97
	v_add_f32_e32 v96, v96, v98
	v_fmac_f32_e32 v99, v104, v104
	v_add_f32_e32 v96, v99, v96
	v_add_f32_e32 v96, v115, v96
	ds_bpermute_b32 v97, v120, v96
	v_cvt_pk_bf16_f32 v98, v100, v101
	v_cvt_pk_bf16_f32 v99, v102, v103
	v_cvt_pk_bf16_f32 v100, v106, v107
	v_cvt_pk_bf16_f32 v101, v104, v105
	s_waitcnt lgkmcnt(0)
	v_add_f32_e32 v96, v96, v97
	ds_bpermute_b32 v97, v114, v96
	global_store_dwordx4 v[126:127], v[98:101], off offset:256
	s_and_saveexec_b64 s[40:41], s[6:7]
	s_cbranch_execz .LBB0_596
	s_waitcnt lgkmcnt(0)
	v_add_f32_e32 v96, v96, v97
	global_atomic_add_f32 v[112:113], v96, off offset:64
.LBB0_596:
	s_or_b64 exec, exec, s[40:41]
	v_add_co_u32_e32 v242, vcc, 0x100000, v244
	s_nop 1
	v_addc_co_u32_e32 v243, vcc, 0, v245, vcc
	global_load_dwordx4 v[172:175], v[242:243], off nt
	global_load_dwordx4 v[176:179], v[242:243], off offset:16 nt
	global_load_dwordx4 v[180:183], v[242:243], off offset:512 nt
	global_load_dwordx4 v[184:187], v[242:243], off offset:528 nt
	v_add_co_u32_e32 v240, vcc, 0x120000, v244
	s_nop 1
	v_addc_co_u32_e32 v241, vcc, 0, v245, vcc
	global_load_dwordx4 v[188:191], v[240:241], off nt
	global_load_dwordx4 v[196:199], v[240:241], off offset:16 nt
	global_load_dwordx4 v[200:203], v[240:241], off offset:512 nt
	global_load_dwordx4 v[204:207], v[240:241], off offset:528 nt
	v_or_b32_e32 v96, 32, v148
	s_waitcnt lgkmcnt(0)
	v_ashrrev_i32_e32 v97, 31, v96
	v_lshlrev_b64 v[96:97], 11, v[96:97]
	v_lshl_add_u64 v[104:105], v[96:97], 0, v[146:147]
	v_lshl_add_u64 v[106:107], v[104:105], 2, s[10:11]
	s_waitcnt vmcnt(15)
	s_nop 0
	v_mov_b32_e32 v96, v208
	v_mov_b32_e32 v97, v209
	v_mov_b32_e32 v98, v210
	v_mov_b32_e32 v99, v211
	s_waitcnt vmcnt(14)
	s_nop 0
	v_mov_b32_e32 v100, v212
	v_mov_b32_e32 v101, v213
	v_mov_b32_e32 v102, v214
	v_mov_b32_e32 v103, v215
	v_lshl_add_u64 v[104:105], v[104:105], 1, s[14:15]
	v_pk_add_f32 v[98:99], v[94:95], v[98:99]
	v_pk_add_f32 v[96:97], v[92:93], v[96:97]
	v_pk_add_f32 v[102:103], v[90:91], v[102:103]
	v_pk_add_f32 v[100:101], v[88:89], v[100:101]
	v_cvt_pk_bf16_f32 v88, v96, v97
	v_cvt_pk_bf16_f32 v89, v98, v99
	v_mul_f32_e32 v97, v97, v97
	v_cvt_pk_bf16_f32 v90, v100, v101
	v_cvt_pk_bf16_f32 v91, v102, v103
	global_store_dwordx4 v[104:105], v[88:91], off
	s_waitcnt vmcnt(13)
	s_nop 0
	v_mov_b32_e32 v88, v216
	v_mov_b32_e32 v89, v217
	v_mov_b32_e32 v90, v218
	v_mov_b32_e32 v91, v219
	s_nop 0
	s_waitcnt vmcnt(12)
	s_nop 0
	v_mov_b32_e32 v92, v220
	v_mov_b32_e32 v93, v221
	v_mov_b32_e32 v94, v222
	v_mov_b32_e32 v95, v223
	v_mul_f32_e32 v99, v99, v99
	v_mul_f32_e32 v101, v101, v101
	v_fmac_f32_e32 v97, v96, v96
	v_fmac_f32_e32 v99, v98, v98
	v_mul_f32_e32 v103, v103, v103
	v_fmac_f32_e32 v101, v100, v100
	v_add_f32_e32 v96, v97, v99
	v_fmac_f32_e32 v103, v102, v102
	v_add_f32_e32 v96, v96, v101
	v_add_f32_e32 v96, v103, v96
	v_pk_add_f32 v[86:87], v[86:87], v[90:91]
	v_pk_add_f32 v[84:85], v[84:85], v[88:89]
	v_pk_add_f32 v[90:91], v[80:81], v[92:93]
	v_mul_f32_e32 v80, v85, v85
	v_mul_f32_e32 v81, v87, v87
	v_pk_add_f32 v[88:89], v[82:83], v[94:95]
	v_mul_f32_e32 v82, v91, v91
	v_fmac_f32_e32 v80, v84, v84
	v_fmac_f32_e32 v81, v86, v86
	v_mul_f32_e32 v83, v89, v89
	v_fmac_f32_e32 v82, v90, v90
	v_add_f32_e32 v80, v80, v81
	v_add_f32_e32 v80, v80, v82
	v_fmac_f32_e32 v83, v88, v88
	v_add_f32_e32 v80, v83, v80
	v_add_f32_e32 v80, v96, v80
	ds_bpermute_b32 v81, v120, v80
	v_cvt_pk_bf16_f32 v82, v84, v85
	v_cvt_pk_bf16_f32 v83, v86, v87
	v_cvt_pk_bf16_f32 v84, v90, v91
	v_cvt_pk_bf16_f32 v85, v88, v89
	s_waitcnt lgkmcnt(0)
	v_add_f32_e32 v80, v80, v81
	ds_bpermute_b32 v81, v114, v80
	global_store_dwordx4 v[104:105], v[82:85], off offset:256
	s_and_saveexec_b64 s[40:41], s[6:7]
	s_cbranch_execz .LBB0_598
	s_waitcnt lgkmcnt(0)
	v_add_f32_e32 v80, v80, v81
	global_atomic_add_f32 v[112:113], v80, off offset:128
.LBB0_598:
	s_or_b64 exec, exec, s[40:41]
	v_or_b32_e32 v80, 48, v148
	s_waitcnt lgkmcnt(0)
	v_ashrrev_i32_e32 v81, 31, v80
	v_lshlrev_b64 v[80:81], 11, v[80:81]
	v_lshl_add_u64 v[88:89], v[80:81], 0, v[146:147]
	v_lshl_add_u64 v[90:91], v[88:89], 2, s[10:11]
	s_waitcnt vmcnt(11)
	s_nop 0
	v_mov_b32_e32 v80, v224
	v_mov_b32_e32 v81, v225
	v_mov_b32_e32 v82, v226
	v_mov_b32_e32 v83, v227
	s_waitcnt vmcnt(10)
	s_nop 0
	v_mov_b32_e32 v84, v228
	v_mov_b32_e32 v85, v229
	v_mov_b32_e32 v86, v230
	v_mov_b32_e32 v87, v231
	v_lshl_add_u64 v[88:89], v[88:89], 1, s[14:15]
	v_pk_add_f32 v[82:83], v[78:79], v[82:83]
	v_pk_add_f32 v[80:81], v[76:77], v[80:81]
	v_pk_add_f32 v[86:87], v[74:75], v[86:87]
	v_pk_add_f32 v[84:85], v[72:73], v[84:85]
	v_cvt_pk_bf16_f32 v72, v80, v81
	v_cvt_pk_bf16_f32 v73, v82, v83
	v_mul_f32_e32 v81, v81, v81
	v_cvt_pk_bf16_f32 v74, v84, v85
	v_cvt_pk_bf16_f32 v75, v86, v87
	global_store_dwordx4 v[88:89], v[72:75], off
	s_waitcnt vmcnt(9)
	s_nop 0
	v_mov_b32_e32 v72, v232
	v_mov_b32_e32 v73, v233
	v_mov_b32_e32 v74, v234
	v_mov_b32_e32 v75, v235
	s_nop 0
	s_waitcnt vmcnt(8)
	s_nop 0
	v_mov_b32_e32 v76, v236
	v_mov_b32_e32 v77, v237
	v_mov_b32_e32 v78, v238
	v_mov_b32_e32 v79, v239
	v_mul_f32_e32 v83, v83, v83
	v_mul_f32_e32 v85, v85, v85
	v_fmac_f32_e32 v81, v80, v80
	v_fmac_f32_e32 v83, v82, v82
	v_mul_f32_e32 v87, v87, v87
	v_fmac_f32_e32 v85, v84, v84
	v_add_f32_e32 v80, v81, v83
	v_fmac_f32_e32 v87, v86, v86
	v_add_f32_e32 v80, v80, v85
	v_add_f32_e32 v80, v87, v80
	v_pk_add_f32 v[70:71], v[70:71], v[74:75]
	v_pk_add_f32 v[68:69], v[68:69], v[72:73]
	v_pk_add_f32 v[74:75], v[64:65], v[76:77]
	v_mul_f32_e32 v64, v69, v69
	v_mul_f32_e32 v65, v71, v71
	v_pk_add_f32 v[72:73], v[66:67], v[78:79]
	v_mul_f32_e32 v66, v75, v75
	v_fmac_f32_e32 v64, v68, v68
	v_fmac_f32_e32 v65, v70, v70
	v_mul_f32_e32 v67, v73, v73
	v_fmac_f32_e32 v66, v74, v74
	v_add_f32_e32 v64, v64, v65
	v_add_f32_e32 v64, v64, v66
	v_fmac_f32_e32 v67, v72, v72
	v_add_f32_e32 v64, v67, v64
	v_add_f32_e32 v64, v80, v64
	ds_bpermute_b32 v65, v120, v64
	v_cvt_pk_bf16_f32 v66, v68, v69
	v_cvt_pk_bf16_f32 v67, v70, v71
	v_cvt_pk_bf16_f32 v68, v74, v75
	v_cvt_pk_bf16_f32 v69, v72, v73
	s_waitcnt lgkmcnt(0)
	v_add_f32_e32 v64, v64, v65
	ds_bpermute_b32 v65, v114, v64
	global_store_dwordx4 v[88:89], v[66:69], off offset:256
	s_and_saveexec_b64 s[40:41], s[6:7]
	s_cbranch_execz .LBB0_600
	s_waitcnt lgkmcnt(0)
	v_add_f32_e32 v64, v64, v65
	global_atomic_add_f32 v[112:113], v64, off offset:192
.LBB0_600:
	s_or_b64 exec, exec, s[40:41]
	v_add_co_u32_e32 v242, vcc, 0x140000, v244
	s_nop 1
	v_addc_co_u32_e32 v243, vcc, 0, v245, vcc
	global_load_dwordx4 v[208:211], v[242:243], off nt
	global_load_dwordx4 v[212:215], v[242:243], off offset:16 nt
	global_load_dwordx4 v[216:219], v[242:243], off offset:512 nt
	global_load_dwordx4 v[220:223], v[242:243], off offset:528 nt
	v_add_co_u32_e32 v240, vcc, 0x160000, v244
	s_nop 1
	v_addc_co_u32_e32 v241, vcc, 0, v245, vcc
	global_load_dwordx4 v[224:227], v[240:241], off nt
	global_load_dwordx4 v[228:231], v[240:241], off offset:16 nt
	global_load_dwordx4 v[232:235], v[240:241], off offset:512 nt
	global_load_dwordx4 v[236:239], v[240:241], off offset:528 nt
	v_lshl_add_u64 v[72:73], v[144:145], 0, s[22:23]
	v_lshl_add_u64 v[74:75], v[72:73], 2, s[10:11]
	s_waitcnt lgkmcnt(0)
	s_waitcnt vmcnt(15)
	s_nop 0
	v_mov_b32_e32 v64, v172
	v_mov_b32_e32 v65, v173
	v_mov_b32_e32 v66, v174
	v_mov_b32_e32 v67, v175
	s_waitcnt vmcnt(14)
	s_nop 0
	v_mov_b32_e32 v68, v176
	v_mov_b32_e32 v69, v177
	v_mov_b32_e32 v70, v178
	v_mov_b32_e32 v71, v179
	v_lshl_add_u64 v[72:73], v[72:73], 1, s[14:15]
	v_pk_add_f32 v[66:67], v[62:63], v[66:67]
	v_pk_add_f32 v[64:65], v[60:61], v[64:65]
	v_pk_add_f32 v[70:71], v[58:59], v[70:71]
	v_pk_add_f32 v[68:69], v[56:57], v[68:69]
	v_cvt_pk_bf16_f32 v56, v64, v65
	v_cvt_pk_bf16_f32 v57, v66, v67
	v_mul_f32_e32 v65, v65, v65
	v_cvt_pk_bf16_f32 v58, v68, v69
	v_cvt_pk_bf16_f32 v59, v70, v71
	global_store_dwordx4 v[72:73], v[56:59], off
	s_waitcnt vmcnt(13)
	s_nop 0
	v_mov_b32_e32 v56, v180
	v_mov_b32_e32 v57, v181
	v_mov_b32_e32 v58, v182
	v_mov_b32_e32 v59, v183
	s_nop 0
	s_waitcnt vmcnt(12)
	s_nop 0
	v_mov_b32_e32 v60, v184
	v_mov_b32_e32 v61, v185
	v_mov_b32_e32 v62, v186
	v_mov_b32_e32 v63, v187
	v_mul_f32_e32 v67, v67, v67
	v_mul_f32_e32 v69, v69, v69
	v_fmac_f32_e32 v65, v64, v64
	v_fmac_f32_e32 v67, v66, v66
	v_mul_f32_e32 v71, v71, v71
	v_fmac_f32_e32 v69, v68, v68
	v_add_f32_e32 v64, v65, v67
	v_fmac_f32_e32 v71, v70, v70
	v_add_f32_e32 v64, v64, v69
	v_add_f32_e32 v64, v71, v64
	v_pk_add_f32 v[54:55], v[54:55], v[58:59]
	v_pk_add_f32 v[52:53], v[52:53], v[56:57]
	v_pk_add_f32 v[58:59], v[48:49], v[60:61]
	v_mul_f32_e32 v48, v53, v53
	v_mul_f32_e32 v49, v55, v55
	v_pk_add_f32 v[56:57], v[50:51], v[62:63]
	v_mul_f32_e32 v50, v59, v59
	v_fmac_f32_e32 v48, v52, v52
	v_fmac_f32_e32 v49, v54, v54
	v_mul_f32_e32 v51, v57, v57
	v_fmac_f32_e32 v50, v58, v58
	v_add_f32_e32 v48, v48, v49
	v_add_f32_e32 v48, v48, v50
	v_fmac_f32_e32 v51, v56, v56
	v_add_f32_e32 v48, v51, v48
	v_add_f32_e32 v48, v64, v48
	ds_bpermute_b32 v49, v120, v48
	v_cvt_pk_bf16_f32 v50, v52, v53
	v_cvt_pk_bf16_f32 v51, v54, v55
	v_cvt_pk_bf16_f32 v52, v58, v59
	v_cvt_pk_bf16_f32 v53, v56, v57
	s_waitcnt lgkmcnt(0)
	v_add_f32_e32 v48, v48, v49
	ds_bpermute_b32 v49, v114, v48
	global_store_dwordx4 v[72:73], v[50:53], off offset:256
	s_and_saveexec_b64 s[40:41], s[6:7]
	s_cbranch_execz .LBB0_602
	s_waitcnt lgkmcnt(0)
	v_add_f32_e32 v48, v48, v49
	global_atomic_add_f32 v[112:113], v48, off offset:512
.LBB0_602:
	s_or_b64 exec, exec, s[40:41]
	v_lshl_add_u64 v[56:57], v[144:145], 0, s[24:25]
	v_lshl_add_u64 v[58:59], v[56:57], 2, s[10:11]
	s_waitcnt lgkmcnt(0)
	s_waitcnt vmcnt(11)
	s_nop 0
	v_mov_b32_e32 v48, v188
	v_mov_b32_e32 v49, v189
	v_mov_b32_e32 v50, v190
	v_mov_b32_e32 v51, v191
	s_waitcnt vmcnt(10)
	s_nop 0
	v_mov_b32_e32 v52, v196
	v_mov_b32_e32 v53, v197
	v_mov_b32_e32 v54, v198
	v_mov_b32_e32 v55, v199
	v_lshl_add_u64 v[56:57], v[56:57], 1, s[14:15]
	v_pk_add_f32 v[50:51], v[46:47], v[50:51]
	v_pk_add_f32 v[48:49], v[44:45], v[48:49]
	v_pk_add_f32 v[54:55], v[42:43], v[54:55]
	v_pk_add_f32 v[52:53], v[40:41], v[52:53]
	v_cvt_pk_bf16_f32 v40, v48, v49
	v_cvt_pk_bf16_f32 v41, v50, v51
	v_mul_f32_e32 v49, v49, v49
	v_cvt_pk_bf16_f32 v42, v52, v53
	v_cvt_pk_bf16_f32 v43, v54, v55
	global_store_dwordx4 v[56:57], v[40:43], off
	s_waitcnt vmcnt(9)
	s_nop 0
	v_mov_b32_e32 v40, v200
	v_mov_b32_e32 v41, v201
	v_mov_b32_e32 v42, v202
	v_mov_b32_e32 v43, v203
	s_nop 0
	s_waitcnt vmcnt(8)
	s_nop 0
	v_mov_b32_e32 v44, v204
	v_mov_b32_e32 v45, v205
	v_mov_b32_e32 v46, v206
	v_mov_b32_e32 v47, v207
	v_mul_f32_e32 v51, v51, v51
	v_mul_f32_e32 v53, v53, v53
	v_fmac_f32_e32 v49, v48, v48
	v_fmac_f32_e32 v51, v50, v50
	v_mul_f32_e32 v55, v55, v55
	v_fmac_f32_e32 v53, v52, v52
	v_add_f32_e32 v48, v49, v51
	v_fmac_f32_e32 v55, v54, v54
	v_add_f32_e32 v48, v48, v53
	v_add_f32_e32 v48, v55, v48
	v_pk_add_f32 v[38:39], v[38:39], v[42:43]
	v_pk_add_f32 v[36:37], v[36:37], v[40:41]
	v_pk_add_f32 v[42:43], v[32:33], v[44:45]
	v_mul_f32_e32 v32, v37, v37
	v_mul_f32_e32 v33, v39, v39
	v_pk_add_f32 v[40:41], v[34:35], v[46:47]
	v_mul_f32_e32 v34, v43, v43
	v_fmac_f32_e32 v32, v36, v36
	v_fmac_f32_e32 v33, v38, v38
	v_mul_f32_e32 v35, v41, v41
	v_fmac_f32_e32 v34, v42, v42
	v_add_f32_e32 v32, v32, v33
	v_add_f32_e32 v32, v32, v34
	v_fmac_f32_e32 v35, v40, v40
	v_add_f32_e32 v32, v35, v32
	v_add_f32_e32 v32, v48, v32
	ds_bpermute_b32 v33, v120, v32
	v_cvt_pk_bf16_f32 v34, v36, v37
	v_cvt_pk_bf16_f32 v35, v38, v39
	v_cvt_pk_bf16_f32 v36, v42, v43
	v_cvt_pk_bf16_f32 v37, v40, v41
	s_waitcnt lgkmcnt(0)
	v_add_f32_e32 v32, v32, v33
	ds_bpermute_b32 v33, v114, v32
	global_store_dwordx4 v[56:57], v[34:37], off offset:256
	s_and_saveexec_b64 s[40:41], s[6:7]
	s_cbranch_execz .LBB0_604
	s_waitcnt lgkmcnt(0)
	v_add_f32_e32 v32, v32, v33
	global_atomic_add_f32 v[112:113], v32, off offset:576
.LBB0_604:
	s_or_b64 exec, exec, s[40:41]
	v_lshl_add_u64 v[40:41], v[144:145], 0, s[26:27]
	v_lshl_add_u64 v[42:43], v[40:41], 2, s[10:11]
	s_waitcnt lgkmcnt(0)
	s_waitcnt vmcnt(7)
	s_nop 0
	v_mov_b32_e32 v32, v208
	v_mov_b32_e32 v33, v209
	v_mov_b32_e32 v34, v210
	v_mov_b32_e32 v35, v211
	s_waitcnt vmcnt(6)
	s_nop 0
	v_mov_b32_e32 v36, v212
	v_mov_b32_e32 v37, v213
	v_mov_b32_e32 v38, v214
	v_mov_b32_e32 v39, v215
	v_lshl_add_u64 v[40:41], v[40:41], 1, s[14:15]
	v_pk_add_f32 v[34:35], v[30:31], v[34:35]
	v_pk_add_f32 v[32:33], v[28:29], v[32:33]
	v_pk_add_f32 v[38:39], v[26:27], v[38:39]
	v_pk_add_f32 v[36:37], v[24:25], v[36:37]
	v_cvt_pk_bf16_f32 v24, v32, v33
	v_cvt_pk_bf16_f32 v25, v34, v35
	v_mul_f32_e32 v33, v33, v33
	v_cvt_pk_bf16_f32 v26, v36, v37
	v_cvt_pk_bf16_f32 v27, v38, v39
	global_store_dwordx4 v[40:41], v[24:27], off
	s_waitcnt vmcnt(5)
	s_nop 0
	v_mov_b32_e32 v24, v216
	v_mov_b32_e32 v25, v217
	v_mov_b32_e32 v26, v218
	v_mov_b32_e32 v27, v219
	s_nop 0
	s_waitcnt vmcnt(4)
	s_nop 0
	v_mov_b32_e32 v28, v220
	v_mov_b32_e32 v29, v221
	v_mov_b32_e32 v30, v222
	v_mov_b32_e32 v31, v223
	v_mul_f32_e32 v35, v35, v35
	v_mul_f32_e32 v37, v37, v37
	v_fmac_f32_e32 v33, v32, v32
	v_fmac_f32_e32 v35, v34, v34
	v_mul_f32_e32 v39, v39, v39
	v_fmac_f32_e32 v37, v36, v36
	v_add_f32_e32 v32, v33, v35
	v_fmac_f32_e32 v39, v38, v38
	v_add_f32_e32 v32, v32, v37
	v_add_f32_e32 v32, v39, v32
	v_pk_add_f32 v[22:23], v[22:23], v[26:27]
	v_pk_add_f32 v[20:21], v[20:21], v[24:25]
	v_pk_add_f32 v[26:27], v[16:17], v[28:29]
	v_mul_f32_e32 v16, v21, v21
	v_mul_f32_e32 v17, v23, v23
	v_pk_add_f32 v[24:25], v[18:19], v[30:31]
	v_mul_f32_e32 v18, v27, v27
	v_fmac_f32_e32 v16, v20, v20
	v_fmac_f32_e32 v17, v22, v22
	v_mul_f32_e32 v19, v25, v25
	v_fmac_f32_e32 v18, v26, v26
	v_add_f32_e32 v16, v16, v17
	v_add_f32_e32 v16, v16, v18
	v_fmac_f32_e32 v19, v24, v24
	v_add_f32_e32 v16, v19, v16
	v_add_f32_e32 v16, v32, v16
	ds_bpermute_b32 v17, v120, v16
	v_cvt_pk_bf16_f32 v18, v20, v21
	v_cvt_pk_bf16_f32 v19, v22, v23
	v_cvt_pk_bf16_f32 v20, v26, v27
	v_cvt_pk_bf16_f32 v21, v24, v25
	s_waitcnt lgkmcnt(0)
	v_add_f32_e32 v16, v16, v17
	ds_bpermute_b32 v17, v114, v16
	global_store_dwordx4 v[40:41], v[18:21], off offset:256
	s_and_saveexec_b64 s[40:41], s[6:7]
	s_cbranch_execz .LBB0_606
	s_waitcnt lgkmcnt(0)
	v_add_f32_e32 v16, v16, v17
	global_atomic_add_f32 v[112:113], v16, off offset:640
.LBB0_606:
	s_or_b64 exec, exec, s[40:41]
	v_lshl_add_u64 v[24:25], v[144:145], 0, s[28:29]
	v_lshl_add_u64 v[26:27], v[24:25], 2, s[10:11]
	s_waitcnt lgkmcnt(0)
	s_waitcnt vmcnt(3)
	s_nop 0
	v_mov_b32_e32 v16, v224
	v_mov_b32_e32 v17, v225
	v_mov_b32_e32 v18, v226
	v_mov_b32_e32 v19, v227
	s_waitcnt vmcnt(2)
	s_nop 0
	v_mov_b32_e32 v20, v228
	v_mov_b32_e32 v21, v229
	v_mov_b32_e32 v22, v230
	v_mov_b32_e32 v23, v231
	v_lshl_add_u64 v[24:25], v[24:25], 1, s[14:15]
	v_pk_add_f32 v[18:19], v[14:15], v[18:19]
	v_pk_add_f32 v[16:17], v[12:13], v[16:17]
	v_pk_add_f32 v[22:23], v[10:11], v[22:23]
	v_pk_add_f32 v[20:21], v[8:9], v[20:21]
	v_cvt_pk_bf16_f32 v8, v16, v17
	v_cvt_pk_bf16_f32 v9, v18, v19
	v_mul_f32_e32 v17, v17, v17
	v_cvt_pk_bf16_f32 v10, v20, v21
	v_cvt_pk_bf16_f32 v11, v22, v23
	global_store_dwordx4 v[24:25], v[8:11], off
	s_waitcnt vmcnt(1)
	s_nop 0
	v_mov_b32_e32 v8, v232
	v_mov_b32_e32 v9, v233
	v_mov_b32_e32 v10, v234
	v_mov_b32_e32 v11, v235
	s_nop 0
	s_waitcnt vmcnt(0)
	s_nop 0
	v_mov_b32_e32 v12, v236
	v_mov_b32_e32 v13, v237
	v_mov_b32_e32 v14, v238
	v_mov_b32_e32 v15, v239
	v_mul_f32_e32 v19, v19, v19
	v_mul_f32_e32 v21, v21, v21
	v_fmac_f32_e32 v17, v16, v16
	v_fmac_f32_e32 v19, v18, v18
	v_mul_f32_e32 v23, v23, v23
	v_fmac_f32_e32 v21, v20, v20
	v_add_f32_e32 v16, v17, v19
	v_fmac_f32_e32 v23, v22, v22
	v_add_f32_e32 v16, v16, v21
	v_add_f32_e32 v16, v23, v16
	v_pk_add_f32 v[6:7], v[6:7], v[10:11]
	v_pk_add_f32 v[4:5], v[4:5], v[8:9]
	v_pk_add_f32 v[10:11], v[0:1], v[12:13]
	v_mul_f32_e32 v0, v5, v5
	v_mul_f32_e32 v1, v7, v7
	v_pk_add_f32 v[8:9], v[2:3], v[14:15]
	v_mul_f32_e32 v2, v11, v11
	v_fmac_f32_e32 v0, v4, v4
	v_fmac_f32_e32 v1, v6, v6
	v_mul_f32_e32 v3, v9, v9
	v_fmac_f32_e32 v2, v10, v10
	v_add_f32_e32 v0, v0, v1
	v_add_f32_e32 v0, v0, v2
	v_fmac_f32_e32 v3, v8, v8
	v_add_f32_e32 v0, v3, v0
	v_add_f32_e32 v0, v16, v0
	ds_bpermute_b32 v1, v120, v0
	v_cvt_pk_bf16_f32 v2, v4, v5
	v_cvt_pk_bf16_f32 v3, v6, v7
	v_cvt_pk_bf16_f32 v4, v10, v11
	v_cvt_pk_bf16_f32 v5, v8, v9
	s_waitcnt lgkmcnt(0)
	v_add_f32_e32 v0, v0, v1
	ds_bpermute_b32 v1, v114, v0
	global_store_dwordx4 v[24:25], v[2:5], off offset:256
	s_and_saveexec_b64 s[40:41], s[6:7]
	s_cbranch_execz .LBB0_608
	s_waitcnt lgkmcnt(0)
	v_add_f32_e32 v0, v0, v1
	global_atomic_add_f32 v[112:113], v0, off offset:704

.LBB0_1330:
	s_or_b64 exec, exec, s[6:7]
	v_mov_b32_e32 v1, v192
	s_waitcnt lgkmcnt(0)
	s_barrier
	s_cmpk_gt_i32 s2, 0x1ff
	v_readfirstlane_b32 s6, v1
	s_cbranch_scc1 .LBB0_1349
	v_ashrrev_i32_e32 v193, 4, v1
	v_add_u32_e32 v194, 32, v193
	s_ashr_i32 s10, s6, 6
	v_and_b32_e32 v7, 0xfffff0, v193
	v_lshlrev_b32_e32 v8, 1, v193
	v_and_b32_e32 v10, 0xfffff0, v194
	s_waitcnt vmcnt(14)
	v_lshlrev_b32_e32 v12, 1, v194
	v_and_b32_e32 v3, 63, v1
	v_and_b32_e32 v187, 31, v1
	s_lshl_b32 s22, s10, 5
	v_lshlrev_b32_e32 v6, 3, v1
	v_and_or_b32 v7, v8, 8, v7
	v_and_or_b32 v10, v12, 8, v10
	v_or_b32_e32 v0, s22, v187
	s_movk_i32 s23, 0x3000
	v_and_b32_e32 v4, 0x78, v6
	v_lshrrev_b32_e32 v8, 1, v193
	v_lshrrev_b32_e32 v7, 1, v7
	v_bfe_u32 v6, v6, 5, 2
	v_and_b32_e32 v9, 3, v193
	v_lshrrev_b32_e32 v10, 1, v10
	v_lshlrev_b32_e32 v12, 4, v3
	v_mad_i64_i32 v[160:161], s[6:7], v0, s23, 0
	v_or_b32_e32 v7, v7, v6
	v_and_or_b32 v8, v8, 4, v9
	v_or_b32_e32 v6, v10, v6
	v_lshlrev_b32_e32 v10, 3, v3
	v_and_b32_e32 v13, 0xc0, v12
	v_lshlrev_b32_e32 v14, 1, v1
	v_bfe_u32 v5, v1, 5, 1
	v_and_or_b32 v13, v10, 24, v13
	v_and_b32_e32 v14, 32, v14
	v_and_b32_e32 v10, 0x100, v10
	s_lshl_b32 s7, s10, 2
	v_lshl_add_u32 v8, v8, 6, 0
	v_lshlrev_b32_e32 v9, 1, v4
	v_or3_b32 v10, v13, v14, v10
	s_add_i32 s24, s7, 0
	v_lshl_add_u32 v13, v6, 9, v8
	s_movk_i32 s7, 0x70
	v_lshlrev_b32_e32 v6, 4, v5
	v_and_b32_e32 v11, 48, v9
	v_lshl_add_u32 v7, v7, 9, v8
	v_bitop3_b32 v9, v9, v1, s7 bitop3:0x78
	v_and_b32_e32 v8, 0x70, v12
	s_waitcnt vmcnt(12)
	v_bitop3_b32 v21, v6, v12, s7 bitop3:0x78
	s_movk_i32 s7, 0x60
	s_movk_i32 s6, 0xc0
	s_waitcnt vmcnt(11)
	v_bitop3_b32 v25, v6, v8, s7 bitop3:0x36
	s_movk_i32 s7, 0x80
	v_bitop3_b32 v26, v6, v8, s7 bitop3:0x36
	s_movk_i32 s7, 0xa0
	s_waitcnt vmcnt(10)
	v_bitop3_b32 v28, v6, v8, s6 bitop3:0x36
	s_movk_i32 s6, 0xe0
	s_mulk_i32 s10, 0x2200
	v_lshlrev_b32_e32 v2, 3, v5
	v_bitop3_b32 v27, v6, v8, s7 bitop3:0x36
	v_bitop3_b32 v29, v6, v8, s6 bitop3:0x36
	v_lshlrev_b32_e32 v196, 2, v5
	v_cmp_gt_u32_e64 s[6:7], 32, v3
	v_cmp_eq_u32_e64 s[8:9], 0, v3
	s_add_i32 s10, s10, 0
	v_lshlrev_b32_e32 v3, 1, v187
	v_mul_u32_u24_e32 v5, 0x440, v5
	v_add3_u32 v197, s10, v3, v5
	v_and_b32_e32 v3, 15, v1
	v_bfe_u32 v1, v1, 4, 2
	v_bitop3_b32 v23, v6, v8, 32 bitop3:0x36
	v_bitop3_b32 v24, v6, v8, 64 bitop3:0x36
	v_lshlrev_b32_e32 v162, 4, v3
	v_lshlrev_b32_e32 v8, 11, v1
	v_mov_b32_e32 v0, 0
	v_add_u32_e32 v195, 0, v10
	v_lshl_add_u32 v15, v193, 8, 0
	v_lshl_add_u32 v17, v194, 8, 0
	v_lshl_add_u32 v19, v187, 8, 0
	v_add_u32_e32 v5, s10, v162
	v_lshlrev_b32_e32 v6, 3, v3
	v_mul_u32_u24_e32 v3, 0x110, v1
	v_or_b32_e32 v10, 0x2000, v8
	v_or_b32_e32 v12, 0x4000, v8
	v_or_b32_e32 v14, 0x6000, v8
	v_or_b32_e32 v16, 0x8000, v8
	v_or_b32_e32 v18, 0xa000, v8
	v_or_b32_e32 v20, 0xc000, v8
	v_or_b32_e32 v22, 0xe000, v8
	s_lshl_b32 s25, s2, 8
	s_lshl_b32 s26, s52, 8
	v_mov_b32_e32 v163, v0
	s_lshl_b32 s27, s2, 4
	v_add_u32_e32 v198, 0xa0, v193
	v_add_u32_e32 v199, 0x80, v193
	v_lshlrev_b32_e32 v164, 1, v2
	v_lshlrev_b32_e32 v166, 1, v4
	v_add_u32_e32 v200, v7, v11
	v_add_u32_e32 v201, v13, v11
	v_add_u32_e32 v202, v15, v9
	v_add_u32_e32 v203, v17, v9
	v_add_u32_e32 v204, v19, v21
	v_add_u32_e32 v205, v19, v23
	v_add_u32_e32 v206, v19, v24
	v_add_u32_e32 v207, v19, v25
	v_add_u32_e32 v208, v19, v26
	v_add_u32_e32 v209, v19, v27
	v_add_u32_e32 v210, v19, v28
	v_add_u32_e32 v211, v19, v29
	v_lshlrev_b32_e32 v168, 1, v6
	s_mov_b64 s[16:17], 0x19800000
	v_add_u32_e32 v212, v5, v3
	v_lshlrev_b32_e32 v170, 1, v8
	v_lshlrev_b32_e32 v172, 1, v10
	v_lshlrev_b32_e32 v174, 1, v12
	v_lshlrev_b32_e32 v176, 1, v14
	v_lshlrev_b32_e32 v178, 1, v16
	v_lshlrev_b32_e32 v180, 1, v18
	v_lshlrev_b32_e32 v182, 1, v20
	v_lshlrev_b32_e32 v184, 1, v22
	v_mov_b32_e32 v213, 0x3000
	v_mov_b32_e32 v165, v0
	v_mov_b32_e32 v167, v0
	v_mbcnt_lo_u32_b32 v214, -1, 0
	s_mov_b32 s29, s3
	s_mov_b32 s30, s2
	s_movk_i32 s28, 0x200
	s_cmp_eq_u32 s99, 0
	s_cbranch_scc1 .Lattn_order_done
	s_and_b32 s26, s2, 7
	s_lshl_b32 s26, s26, 2
	s_lshr_b32 s28, s2, 3
	s_and_b32 s30, s28, 3
	s_add_i32 s26, s26, s30
	s_lshr_b32 s28, s28, 2
	s_lshl_b32 s28, s28, 4
	s_lshr_b32 s30, s26, 4
	s_lshl_b32 s30, s30, 8
	s_and_b32 s26, s26, 15
	s_add_i32 s30, s30, s26
	s_add_i32 s30, s30, s28
	s_lshl_b32 s29, s30, 3
	s_lshl_b32 s25, s30, 8
	s_lshl_b32 s27, s30, 4
	s_add_i32 s28, s30, 0x100
	s_mov_b32 s26, 0x8000
.Lattn_order_done:
	s_branch .LBB0_1333
.LBB0_1332:
	v_cvt_pk_bf16_f32 v1, v64, v0
	ds_write_b16 v197, v1 offset:36864
	v_cvt_pk_bf16_f32 v1, v48, v0
	ds_write_b16 v197, v1 offset:36928
	v_cvt_pk_bf16_f32 v1, v32, v0
	ds_write_b16 v197, v1 offset:36992
	v_cvt_pk_bf16_f32 v1, v16, v0
	ds_write_b16 v197, v1 offset:37056
	v_cvt_pk_bf16_f32 v1, v65, v0
	ds_write_b16 v197, v1 offset:37136
	v_cvt_pk_bf16_f32 v1, v49, v0
	ds_write_b16 v197, v1 offset:37200
	v_cvt_pk_bf16_f32 v1, v33, v0
	ds_write_b16 v197, v1 offset:37264
	v_cvt_pk_bf16_f32 v1, v17, v0
	ds_write_b16 v197, v1 offset:37328
	v_cvt_pk_bf16_f32 v1, v66, v0
	ds_write_b16 v197, v1 offset:37408
	v_cvt_pk_bf16_f32 v1, v50, v0
	ds_write_b16 v197, v1 offset:37472
	v_cvt_pk_bf16_f32 v1, v34, v0
	ds_write_b16 v197, v1 offset:37536
	v_cvt_pk_bf16_f32 v1, v18, v0
	ds_write_b16 v197, v1 offset:37600
	v_cvt_pk_bf16_f32 v1, v67, v0
	ds_write_b16 v197, v1 offset:37680
	v_cvt_pk_bf16_f32 v1, v51, v0
	ds_write_b16 v197, v1 offset:37744
	v_cvt_pk_bf16_f32 v1, v35, v0
	ds_write_b16 v197, v1 offset:37808
	v_cvt_pk_bf16_f32 v1, v19, v0
	ds_write_b16 v197, v1 offset:37872
	v_cvt_pk_bf16_f32 v1, v68, v0
	ds_write_b16 v197, v1 offset:39040
	v_cvt_pk_bf16_f32 v1, v52, v0
	ds_write_b16 v197, v1 offset:39104
	v_cvt_pk_bf16_f32 v1, v36, v0
	ds_write_b16 v197, v1 offset:39168
	v_cvt_pk_bf16_f32 v1, v20, v0
	ds_write_b16 v197, v1 offset:39232
	v_cvt_pk_bf16_f32 v1, v69, v0
	ds_write_b16 v197, v1 offset:39312
	v_cvt_pk_bf16_f32 v1, v53, v0
	ds_write_b16 v197, v1 offset:39376
	v_cvt_pk_bf16_f32 v1, v37, v0
	ds_write_b16 v197, v1 offset:39440
	v_cvt_pk_bf16_f32 v1, v21, v0
	ds_write_b16 v197, v1 offset:39504
	v_cvt_pk_bf16_f32 v1, v70, v0
	ds_write_b16 v197, v1 offset:39584
	v_cvt_pk_bf16_f32 v1, v54, v0
	ds_write_b16 v197, v1 offset:39648
	v_cvt_pk_bf16_f32 v1, v38, v0
	ds_write_b16 v197, v1 offset:39712
	v_cvt_pk_bf16_f32 v1, v22, v0
	ds_write_b16 v197, v1 offset:39776
	v_cvt_pk_bf16_f32 v1, v71, v0
	ds_write_b16 v197, v1 offset:39856
	v_cvt_pk_bf16_f32 v1, v55, v0
	ds_write_b16 v197, v1 offset:39920
	v_cvt_pk_bf16_f32 v1, v39, v0
	ds_write_b16 v197, v1 offset:39984
	v_cvt_pk_bf16_f32 v1, v23, v0
	ds_write_b16 v197, v1 offset:40048
	v_cvt_pk_bf16_f32 v1, v72, v0
	ds_write_b16 v197, v1 offset:41216
	v_cvt_pk_bf16_f32 v1, v56, v0
	ds_write_b16 v197, v1 offset:41280
	v_cvt_pk_bf16_f32 v1, v40, v0
	ds_write_b16 v197, v1 offset:41344
	v_cvt_pk_bf16_f32 v1, v24, v0
	ds_write_b16 v197, v1 offset:41408
	v_cvt_pk_bf16_f32 v1, v73, v0
	ds_write_b16 v197, v1 offset:41488
	v_cvt_pk_bf16_f32 v1, v57, v0
	ds_write_b16 v197, v1 offset:41552
	v_cvt_pk_bf16_f32 v1, v41, v0
	ds_write_b16 v197, v1 offset:41616
	v_cvt_pk_bf16_f32 v1, v25, v0
	ds_write_b16 v197, v1 offset:41680
	v_cvt_pk_bf16_f32 v1, v74, v0
	ds_write_b16 v197, v1 offset:41760
	v_cvt_pk_bf16_f32 v1, v58, v0
	ds_write_b16 v197, v1 offset:41824
	v_cvt_pk_bf16_f32 v1, v42, v0
	ds_write_b16 v197, v1 offset:41888
	v_cvt_pk_bf16_f32 v1, v26, v0
	ds_write_b16 v197, v1 offset:41952
	v_cvt_pk_bf16_f32 v1, v75, v0
	ds_write_b16 v197, v1 offset:42032
	v_cvt_pk_bf16_f32 v1, v59, v0
	ds_write_b16 v197, v1 offset:42096
	v_cvt_pk_bf16_f32 v1, v43, v0
	ds_write_b16 v197, v1 offset:42160
	v_cvt_pk_bf16_f32 v1, v27, v0
	ds_write_b16 v197, v1 offset:42224
	v_cvt_pk_bf16_f32 v1, v76, v0
	ds_write_b16 v197, v1 offset:43392
	v_cvt_pk_bf16_f32 v1, v60, v0
	ds_write_b16 v197, v1 offset:43456
	v_cvt_pk_bf16_f32 v1, v44, v0
	ds_write_b16 v197, v1 offset:43520
	v_cvt_pk_bf16_f32 v1, v28, v0
	ds_write_b16 v197, v1 offset:43584
	v_cvt_pk_bf16_f32 v1, v77, v0
	ds_write_b16 v197, v1 offset:43664
	v_cvt_pk_bf16_f32 v1, v61, v0
	ds_write_b16 v197, v1 offset:43728
	v_cvt_pk_bf16_f32 v1, v45, v0
	ds_write_b16 v197, v1 offset:43792
	v_cvt_pk_bf16_f32 v1, v29, v0
	ds_write_b16 v197, v1 offset:43856
	v_cvt_pk_bf16_f32 v1, v78, v0
	ds_write_b16 v197, v1 offset:43936
	v_cvt_pk_bf16_f32 v1, v62, v0
	s_add_i32 s10, s37, s22
	ds_write_b16 v197, v1 offset:44000
	v_cvt_pk_bf16_f32 v1, v46, v0
	s_ashr_i32 s11, s10, 31
	ds_write_b16 v197, v1 offset:44064
	v_cvt_pk_bf16_f32 v1, v30, v0
	s_lshl_b64 s[10:11], s[10:11], 12
	ds_write_b16 v197, v1 offset:44128
	v_cvt_pk_bf16_f32 v1, v79, v0
	s_add_u32 s10, s18, s10
	ds_write_b16 v197, v1 offset:44208
	v_cvt_pk_bf16_f32 v1, v63, v0
	s_addc_u32 s11, s19, s11
	ds_write_b16 v197, v1 offset:44272
	v_cvt_pk_bf16_f32 v1, v47, v0
	s_lshl_b32 s12, s31, 1
	ds_write_b16 v197, v1 offset:44336
	v_cvt_pk_bf16_f32 v1, v31, v0
	ds_write_b16 v197, v1 offset:44400
	s_add_u32 s10, s10, s12
	s_addc_u32 s11, s11, 0
	s_waitcnt lgkmcnt(0)
	v_mov_b32_e32 v169, v0
	v_lshl_add_u64 v[6:7], s[10:11], 0, v[168:169]
	ds_read_b128 v[2:5], v212 offset:36864
	v_lshl_add_u64 v[10:11], v[6:7], 0, s[16:17]
	ds_read_b128 v[6:9], v212 offset:37952
	v_mov_b32_e32 v171, v0
	v_lshl_add_u64 v[12:13], v[10:11], 0, v[170:171]
	v_mov_b32_e32 v173, v0
	s_waitcnt lgkmcnt(1)
	global_store_dwordx4 v[12:13], v[2:5], off
	v_lshl_add_u64 v[12:13], v[10:11], 0, v[172:173]
	ds_read_b128 v[2:5], v212 offset:39040
	s_waitcnt lgkmcnt(1)
	global_store_dwordx4 v[12:13], v[6:9], off
	ds_read_b128 v[6:9], v212 offset:40128
	v_mov_b32_e32 v175, v0
	v_lshl_add_u64 v[12:13], v[10:11], 0, v[174:175]
	v_mov_b32_e32 v177, v0
	s_waitcnt lgkmcnt(1)
	global_store_dwordx4 v[12:13], v[2:5], off
	v_lshl_add_u64 v[12:13], v[10:11], 0, v[176:177]
	ds_read_b128 v[2:5], v212 offset:41216
	s_waitcnt lgkmcnt(1)
	global_store_dwordx4 v[12:13], v[6:9], off
	ds_read_b128 v[6:9], v212 offset:42304
	v_mov_b32_e32 v179, v0
	v_lshl_add_u64 v[12:13], v[10:11], 0, v[178:179]
	v_mov_b32_e32 v181, v0
	s_waitcnt lgkmcnt(1)
	global_store_dwordx4 v[12:13], v[2:5], off
	v_lshl_add_u64 v[12:13], v[10:11], 0, v[180:181]
	ds_read_b128 v[2:5], v212 offset:43392
	s_waitcnt lgkmcnt(1)
	global_store_dwordx4 v[12:13], v[6:9], off
	ds_read_b128 v[6:9], v212 offset:44480
	v_mov_b32_e32 v183, v0
	v_lshl_add_u64 v[12:13], v[10:11], 0, v[182:183]
	v_mov_b32_e32 v185, v0
	s_add_i32 s25, s25, s26
	s_lshr_b32 s30, s25, 8
	s_lshl_b32 s27, s30, 4
	s_lshl_b32 s29, s30, 3
	s_waitcnt lgkmcnt(1)
	global_store_dwordx4 v[12:13], v[2:5], off
	s_cmp_ge_i32 s30, s28
	s_nop 0
	v_lshl_add_u64 v[2:3], v[10:11], 0, v[184:185]
	s_waitcnt lgkmcnt(0)
	global_store_dwordx4 v[2:3], v[6:9], off
	s_barrier
	s_cbranch_scc1 .LBB0_1349
